# load de-serialisation also in the convert_weights loops (per straight-line block, loads issued together)
# speedup vs baseline: 1.0206x; 1.0030x over previous
; DI int get_tid() { int t = threadIdx.x; asm volatile("" : "+v"(t)); return t; }
; DI unsigned pk2(float a, float b) { f32x2_t f = {a, b}; return __builtin_bit_cast(unsigned, __builtin_convertvector(f, bf16x2_t)); }
; DI void tconv_tile(const float* __restrict__ src, long lds, int cvalid, u16* __restrict__ dst, long ldd, int r0, int c0, char* smem) {
;   float (*T)[65] = (float (*)[65])smem;
;   const int tid = get_tid();
;   __syncthreads();
;   const int lr = tid >> 4, lc = (tid & 15) * 4;
; #pragma unroll
;   for (int i = 0; i < 4; ++i) {
;     const int r = lr + 16 * i;
;     float4 v = make_float4(0.f, 0.f, 0.f, 0.f);
;     if (c0 + lc < cvalid) v = *(const float4*)(src + (long)(r0 + r) * lds + c0 + lc);
;     T[r][lc] = v.x; T[r][lc + 1] = v.y; T[r][lc + 2] = v.z; T[r][lc + 3] = v.w;
;   }
;   __syncthreads();
;   const int oc = tid >> 2, seg = (tid & 3) * 16;
;   unsigned pk[8];
; #pragma unroll
;   for (int k = 0; k < 8; ++k) pk[k] = pk2(T[seg + 2 * k][oc], T[seg + 2 * k + 1][oc]);
;   uint4* d = (uint4*)(dst + (long)(c0 + oc) * ldd + r0 + seg);
;   d[0] = make_uint4(pk[0], pk[1], pk[2], pk[3]);
;   d[1] = make_uint4(pk[4], pk[5], pk[6], pk[7]);
; }
; DI void convert_weights(const Params& p, int layer, char* smem) {
;     ...
;       } else if (t < 976) {
;         const int u = t - 720;
;         tconv_tile(p.w_o + (size_t)o * 1024 * 1024, 1024, 1024, W + WO_O, 1024, (u >> 4) * 64, (u & 15) * 64, smem);
.LBB0_263:
	s_and_b64 vcc, exec, s[38:39]
	s_cbranch_vccz .LBB0_265
	s_and_b32 s14, s5, 0x3c0
	v_mov_b32_e32 v9, v185
	s_and_b32 s13, s8, 0x7fffffc0
	s_lshl_b32 s15, s14, 2
	v_ashrrev_i32_e32 v4, 4, v9
	v_readlane_b32 s16, v252, 63
	v_lshlrev_b32_e32 v14, 4, v9
	s_add_u32 s16, s16, s15
	v_readlane_b32 s15, v253, 0
	v_add_u32_e32 v10, s13, v4
	v_and_b32_e32 v182, 0xf0, v14
	s_addc_u32 s17, s15, 0
	v_ashrrev_i32_e32 v11, 31, v10
	v_lshl_add_u64 v[6:7], s[16:17], 0, v[182:183]
	v_lshlrev_b64 v[2:3], 12, v[10:11]
	v_lshl_add_u64 v[2:3], v[6:7], 0, v[2:3]
	s_movk_i32 s15, 0x104
	s_barrier
	global_load_dwordx4 v[100:103], v[2:3], off
	v_add_u32_e32 v104, 16, v10
	v_ashrrev_i32_e32 v105, 31, v104
	v_lshlrev_b64 v[106:107], 12, v[104:105]
	v_lshl_add_u64 v[108:109], v[6:7], 0, v[106:107]
	global_load_dwordx4 v[110:113], v[108:109], off
	v_add_u32_e32 v114, 32, v10
	v_ashrrev_i32_e32 v115, 31, v114
	v_lshlrev_b64 v[116:117], 12, v[114:115]
	v_lshl_add_u64 v[118:119], v[6:7], 0, v[116:117]
	global_load_dwordx4 v[120:123], v[118:119], off
	v_add_u32_e32 v124, 48, v10
	v_ashrrev_i32_e32 v125, 31, v124
	v_lshlrev_b64 v[126:127], 12, v[124:125]
	v_lshl_add_u64 v[128:129], v[6:7], 0, v[126:127]
	global_load_dwordx4 v[130:133], v[128:129], off
	v_mad_u64_u32 v[12:13], s[16:17], v4, s15, v[182:183]
	s_nop 0
	v_add_u32_e32 v11, 0x1040, v12
	v_and_b32_e32 v14, 48, v14
	v_ashrrev_i32_e32 v15, 2, v9
	s_lshl_b32 s34, s13, 1
	v_lshlrev_b32_e32 v182, 1, v14
	s_waitcnt vmcnt(3)
	ds_write2_b32 v12, v100, v101 offset1:1
	ds_write2_b32 v12, v102, v103 offset0:2 offset1:3
	s_nop 0
	s_nop 0
	s_nop 0
	s_nop 0
	s_nop 0
	s_waitcnt vmcnt(2)
	ds_write2_b32 v11, v110, v111 offset1:1
	v_add_u32_e32 v2, 0x1048, v12
	ds_write2_b32 v2, v112, v113 offset1:1
	s_nop 0
	s_nop 0
	s_nop 0
	s_nop 0
	s_nop 0
	v_add_u32_e32 v11, 0x2080, v12
	s_waitcnt vmcnt(1)
	ds_write2_b32 v11, v120, v121 offset1:1
	v_add_u32_e32 v2, 0x2088, v12
	ds_write2_b32 v2, v122, v123 offset1:1
	s_nop 0
	s_nop 0
	s_nop 0
	s_nop 0
	s_nop 0
	v_add_u32_e32 v6, 0x30c0, v12
	s_waitcnt vmcnt(0)
	ds_write2_b32 v6, v130, v131 offset1:1
	v_add_u32_e32 v2, 0x30c8, v12
	ds_write2_b32 v2, v132, v133 offset1:1
	v_and_b32_e32 v2, -4, v9
	v_mad_u32_u24 v9, v14, s15, v2
	s_waitcnt lgkmcnt(0)
	v_mov_b32_e32 v3, v131
	v_mov_b32_e32 v4, v132
	v_mov_b32_e32 v5, v133
	s_barrier
	ds_read2_b32 v[2:3], v9 offset1:65
	ds_read2_b32 v[4:5], v9 offset0:130 offset1:195
	v_add_u32_e32 v6, 0x400, v9
	v_add_u32_e32 v11, 0x800, v9
	v_add_u32_e32 v9, 0xc00, v9
	s_waitcnt lgkmcnt(1)
	v_cvt_pk_bf16_f32 v2, v2, v3
	s_waitcnt lgkmcnt(0)
	v_cvt_pk_bf16_f32 v3, v4, v5
	ds_read2_b32 v[4:5], v6 offset0:4 offset1:69
	ds_read2_b32 v[6:7], v6 offset0:134 offset1:199
	s_waitcnt lgkmcnt(1)
	v_cvt_pk_bf16_f32 v4, v4, v5
	s_waitcnt lgkmcnt(0)
	v_cvt_pk_bf16_f32 v5, v6, v7
	ds_read2_b32 v[6:7], v11 offset0:8 offset1:73
	s_waitcnt lgkmcnt(0)
	v_cvt_pk_bf16_f32 v10, v6, v7
	ds_read2_b32 v[6:7], v11 offset0:138 offset1:203
	s_waitcnt lgkmcnt(0)
	v_cvt_pk_bf16_f32 v11, v6, v7
	ds_read2_b32 v[6:7], v9 offset0:12 offset1:77
	s_waitcnt lgkmcnt(0)
	v_cvt_pk_bf16_f32 v12, v6, v7
	ds_read2_b32 v[6:7], v9 offset0:142 offset1:207
	s_waitcnt lgkmcnt(0)
	v_cvt_pk_bf16_f32 v13, v6, v7
	v_add_u32_e32 v6, s14, v15
	v_ashrrev_i32_e32 v7, 31, v6
	v_readlane_b32 s14, v252, 26
	v_lshlrev_b64 v[6:7], 11, v[6:7]
	v_readlane_b32 s15, v252, 27
	s_nop 1
	v_lshl_add_u64 v[6:7], s[14:15], 0, v[6:7]
	v_lshl_add_u64 v[6:7], v[6:7], 0, s[34:35]
	v_lshl_add_u64 v[6:7], v[6:7], 0, v[182:183]
	global_store_dwordx4 v[6:7], v[2:5], off
	global_store_dwordx4 v[6:7], v[10:13], off offset:16

; DI int get_tid() { int t = threadIdx.x; asm volatile("" : "+v"(t)); return t; }
; DI unsigned pk2(float a, float b) { f32x2_t f = {a, b}; return __builtin_bit_cast(unsigned, __builtin_convertvector(f, bf16x2_t)); }
; DI void tconv_tile(const float* __restrict__ src, long lds, int cvalid, u16* __restrict__ dst, long ldd, int r0, int c0, char* smem) {
;   float (*T)[65] = (float (*)[65])smem;
;   const int tid = get_tid();
;   __syncthreads();
;   const int lr = tid >> 4, lc = (tid & 15) * 4;
; #pragma unroll
;   for (int i = 0; i < 4; ++i) {
;     const int r = lr + 16 * i;
;     float4 v = make_float4(0.f, 0.f, 0.f, 0.f);
;     if (c0 + lc < cvalid) v = *(const float4*)(src + (long)(r0 + r) * lds + c0 + lc);
;     T[r][lc] = v.x; T[r][lc + 1] = v.y; T[r][lc + 2] = v.z; T[r][lc + 3] = v.w;
;   }
;   __syncthreads();
;   const int oc = tid >> 2, seg = (tid & 3) * 16;
;   unsigned pk[8];
; #pragma unroll
;   for (int k = 0; k < 8; ++k) pk[k] = pk2(T[seg + 2 * k][oc], T[seg + 2 * k + 1][oc]);
;   uint4* d = (uint4*)(dst + (long)(c0 + oc) * ldd + r0 + seg);
;   d[0] = make_uint4(pk[0], pk[1], pk[2], pk[3]);
;   d[1] = make_uint4(pk[4], pk[5], pk[6], pk[7]);
; }
; DI void convert_weights(const Params& p, int layer, char* smem) {
;     ...
;       } else if (t < 720) {
;         const int u = t - 592;
;         const int c0 = (u & 31) * 64, hh = c0 >> 8, j0 = c0 & 255;
;         const int drow0 = j0 < 128 ? hh * 128 + j0 : 1024 + hh * 128 + (j0 - 128);
;         tconv_tile(p.w_kv_up + (size_t)o * 256 * 2048, 2048, 2048, W + WO_KV + (long)(drow0 - c0) * 256, 256, (u >> 5) * 64, c0, smem);
.LBB0_266:
	s_andn2_b64 vcc, exec, s[38:39]
	s_cbranch_vccnz .LBB0_268
	s_add_i32 s13, s5, 0xffff6c00
	s_and_b32 s14, s13, 0x7c0
	s_and_b32 s13, s13, 0xc0
	s_and_b32 s15, s11, 0x380
	s_or_b32 s16, s15, s13
	s_add_i32 s15, s13, s15
	s_addk_i32 s15, 0x380
	s_cmpk_lt_u32 s13, 0x80
	s_cselect_b32 s13, s16, s15
	s_sub_i32 s16, s13, s14
	s_ashr_i32 s17, s16, 31
	s_lshl_b64 s[16:17], s[16:17], 9
	s_add_u32 s38, s87, s16
	v_mov_b32_e32 v9, v185
	s_addc_u32 s39, s90, s17
	s_and_b32 s13, s9, 0x7fffffc0
	s_lshl_b32 s15, s14, 2
	v_ashrrev_i32_e32 v4, 4, v9
	v_readlane_b32 s16, v253, 1
	v_lshlrev_b32_e32 v14, 4, v9
	s_add_u32 s16, s16, s15
	v_readlane_b32 s15, v253, 2
	v_add_u32_e32 v10, s13, v4
	v_and_b32_e32 v182, 0xf0, v14
	s_addc_u32 s17, s15, 0
	v_ashrrev_i32_e32 v11, 31, v10
	v_lshl_add_u64 v[6:7], s[16:17], 0, v[182:183]
	v_lshlrev_b64 v[2:3], 13, v[10:11]
	v_lshl_add_u64 v[2:3], v[6:7], 0, v[2:3]
	s_movk_i32 s15, 0x104
	s_barrier
	global_load_dwordx4 v[100:103], v[2:3], off
	v_add_u32_e32 v104, 16, v10
	v_ashrrev_i32_e32 v105, 31, v104
	v_lshlrev_b64 v[106:107], 13, v[104:105]
	v_lshl_add_u64 v[108:109], v[6:7], 0, v[106:107]
	global_load_dwordx4 v[110:113], v[108:109], off
	v_add_u32_e32 v114, 32, v10
	v_ashrrev_i32_e32 v115, 31, v114
	v_lshlrev_b64 v[116:117], 13, v[114:115]
	v_lshl_add_u64 v[118:119], v[6:7], 0, v[116:117]
	global_load_dwordx4 v[120:123], v[118:119], off
	v_add_u32_e32 v124, 48, v10
	v_ashrrev_i32_e32 v125, 31, v124
	v_lshlrev_b64 v[126:127], 13, v[124:125]
	v_lshl_add_u64 v[128:129], v[6:7], 0, v[126:127]
	global_load_dwordx4 v[130:133], v[128:129], off
	v_mad_u64_u32 v[12:13], s[16:17], v4, s15, v[182:183]
	s_nop 0
	v_add_u32_e32 v11, 0x1040, v12
	v_and_b32_e32 v14, 48, v14
	v_ashrrev_i32_e32 v15, 2, v9
	s_lshl_b32 s34, s13, 1
	v_lshlrev_b32_e32 v182, 1, v14
	s_waitcnt vmcnt(3)
	ds_write2_b32 v12, v100, v101 offset1:1
	ds_write2_b32 v12, v102, v103 offset0:2 offset1:3
	s_nop 0
	s_nop 0
	s_nop 0
	s_nop 0
	s_nop 0
	s_waitcnt vmcnt(2)
	ds_write2_b32 v11, v110, v111 offset1:1
	v_add_u32_e32 v2, 0x1048, v12
	ds_write2_b32 v2, v112, v113 offset1:1
	s_nop 0
	s_nop 0
	s_nop 0
	s_nop 0
	s_nop 0
	v_add_u32_e32 v11, 0x2080, v12
	s_waitcnt vmcnt(1)
	ds_write2_b32 v11, v120, v121 offset1:1
	v_add_u32_e32 v2, 0x2088, v12
	ds_write2_b32 v2, v122, v123 offset1:1
	s_nop 0
	s_nop 0
	s_nop 0
	s_nop 0
	s_nop 0
	v_add_u32_e32 v6, 0x30c0, v12
	s_waitcnt vmcnt(0)
	ds_write2_b32 v6, v130, v131 offset1:1
	v_add_u32_e32 v2, 0x30c8, v12
	ds_write2_b32 v2, v132, v133 offset1:1
	v_and_b32_e32 v2, -4, v9
	v_mad_u32_u24 v9, v14, s15, v2
	s_waitcnt lgkmcnt(0)
	v_mov_b32_e32 v3, v131
	v_mov_b32_e32 v4, v132
	v_mov_b32_e32 v5, v133
	s_barrier
	ds_read2_b32 v[2:3], v9 offset1:65
	ds_read2_b32 v[4:5], v9 offset0:130 offset1:195
	v_add_u32_e32 v6, 0x400, v9
	v_add_u32_e32 v11, 0x800, v9
	v_add_u32_e32 v9, 0xc00, v9
	s_waitcnt lgkmcnt(1)
	v_cvt_pk_bf16_f32 v2, v2, v3
	s_waitcnt lgkmcnt(0)
	v_cvt_pk_bf16_f32 v3, v4, v5
	ds_read2_b32 v[4:5], v6 offset0:4 offset1:69
	ds_read2_b32 v[6:7], v6 offset0:134 offset1:199
	s_waitcnt lgkmcnt(1)
	v_cvt_pk_bf16_f32 v4, v4, v5
	s_waitcnt lgkmcnt(0)
	v_cvt_pk_bf16_f32 v5, v6, v7
	ds_read2_b32 v[6:7], v11 offset0:8 offset1:73
	s_waitcnt lgkmcnt(0)
	v_cvt_pk_bf16_f32 v10, v6, v7
	ds_read2_b32 v[6:7], v11 offset0:138 offset1:203
	s_waitcnt lgkmcnt(0)
	v_cvt_pk_bf16_f32 v11, v6, v7
	ds_read2_b32 v[6:7], v9 offset0:12 offset1:77
	s_waitcnt lgkmcnt(0)
	v_cvt_pk_bf16_f32 v12, v6, v7
	ds_read2_b32 v[6:7], v9 offset0:142 offset1:207
	s_waitcnt lgkmcnt(0)
	v_cvt_pk_bf16_f32 v13, v6, v7
	v_add_u32_e32 v6, s14, v15
	v_ashrrev_i32_e32 v7, 31, v6
	v_lshlrev_b64 v[6:7], 9, v[6:7]
	v_lshl_add_u64 v[6:7], s[38:39], 0, v[6:7]
	v_lshl_add_u64 v[6:7], v[6:7], 0, s[34:35]
	v_lshl_add_u64 v[6:7], v[6:7], 0, v[182:183]
	global_store_dwordx4 v[6:7], v[2:5], off
	global_store_dwordx4 v[6:7], v[10:13], off offset:16

; DI int get_tid() { int t = threadIdx.x; asm volatile("" : "+v"(t)); return t; }
; DI unsigned pk2(float a, float b) { f32x2_t f = {a, b}; return __builtin_bit_cast(unsigned, __builtin_convertvector(f, bf16x2_t)); }
; DI void tconv_tile(const float* __restrict__ src, long lds, int cvalid, u16* __restrict__ dst, long ldd, int r0, int c0, char* smem) {
;   float (*T)[65] = (float (*)[65])smem;
;   const int tid = get_tid();
;   __syncthreads();
;   const int lr = tid >> 4, lc = (tid & 15) * 4;
; #pragma unroll
;   for (int i = 0; i < 4; ++i) {
;     const int r = lr + 16 * i;
;     float4 v = make_float4(0.f, 0.f, 0.f, 0.f);
;     if (c0 + lc < cvalid) v = *(const float4*)(src + (long)(r0 + r) * lds + c0 + lc);
;     T[r][lc] = v.x; T[r][lc + 1] = v.y; T[r][lc + 2] = v.z; T[r][lc + 3] = v.w;
;   }
;   __syncthreads();
;   const int oc = tid >> 2, seg = (tid & 3) * 16;
;   unsigned pk[8];
; #pragma unroll
;   for (int k = 0; k < 8; ++k) pk[k] = pk2(T[seg + 2 * k][oc], T[seg + 2 * k + 1][oc]);
;   uint4* d = (uint4*)(dst + (long)(c0 + oc) * ldd + r0 + seg);
;   d[0] = make_uint4(pk[0], pk[1], pk[2], pk[3]);
;   d[1] = make_uint4(pk[4], pk[5], pk[6], pk[7]);
; }
; DI void convert_weights(const Params& p, int layer, char* smem) {
;     ...
;       } else if (t < 592) {
;         const int u = t - 448;
;         tconv_tile(p.w_q_up + (size_t)o * 384 * 1536, 1536, 1536, W + WO_Q, 384, (u / 24) * 64, (u % 24) * 64, smem);
.LBB0_269:
	s_andn2_b64 vcc, exec, s[38:39]
	s_cbranch_vccnz .LBB0_271
	s_add_i32 s14, s4, 64
	s_and_b32 s13, s14, 0xff
	s_mulk_i32 s13, 0xab
	s_bfe_u32 s13, s13, 0x4000c
	s_mul_i32 s15, s13, 24
	s_sub_i32 s14, s14, s15
	s_and_b32 s16, s14, 0xff
	v_mov_b32_e32 v9, v185
	s_lshl_b32 s14, s16, 8
	v_readlane_b32 s15, v253, 3
	s_add_u32 s14, s15, s14
	v_lshlrev_b32_e32 v12, 4, v9
	v_readlane_b32 s15, v253, 4
	v_ashrrev_i32_e32 v4, 4, v9
	v_and_b32_e32 v182, 0xf0, v12
	s_addc_u32 s15, s15, 0
	v_lshl_add_u64 v[6:7], s[14:15], 0, v[182:183]
	v_lshl_add_u32 v13, s13, 6, v4
	s_movk_i32 s18, 0x1800
	v_mad_i64_i32 v[2:3], s[14:15], v13, s18, v[6:7]
	s_movk_i32 s17, 0x104
	s_barrier
	global_load_dwordx4 v[100:103], v[2:3], off
	v_mad_u64_u32 v[10:11], s[14:15], v4, s17, v[182:183]
	s_nop 0
	v_add_u32_e32 v11, 0x1040, v10
	v_and_b32_e32 v15, 48, v12
	v_ashrrev_i32_e32 v14, 2, v9
	s_lshl_b32 s34, s13, 7
	v_lshlrev_b32_e32 v182, 1, v15
	s_waitcnt vmcnt(0)
	ds_write2_b32 v10, v100, v101 offset1:1
	ds_write2_b32 v10, v102, v103 offset0:2 offset1:3
	v_add_u32_e32 v2, 16, v13
	v_mad_i64_i32 v[2:3], s[14:15], v2, s18, v[6:7]
	global_load_dwordx4 v[2:5], v[2:3], off
	s_waitcnt vmcnt(0)
	ds_write2_b32 v11, v2, v3 offset1:1
	v_add_u32_e32 v2, 0x1048, v10
	ds_write2_b32 v2, v4, v5 offset1:1
	v_add_u32_e32 v2, 32, v13
	v_mad_i64_i32 v[2:3], s[14:15], v2, s18, v[6:7]
	global_load_dwordx4 v[2:5], v[2:3], off
	v_add_u32_e32 v11, 0x2080, v10
	s_waitcnt vmcnt(0)
	ds_write2_b32 v11, v2, v3 offset1:1
	v_add_u32_e32 v2, 0x2088, v10
	ds_write2_b32 v2, v4, v5 offset1:1
	v_add_u32_e32 v2, 48, v13
	v_mad_i64_i32 v[2:3], s[14:15], v2, s18, v[6:7]
	global_load_dwordx4 v[2:5], v[2:3], off
	v_add_u32_e32 v6, 0x30c0, v10
	v_readlane_b32 s14, v252, 29
	v_readlane_b32 s15, v252, 30
	s_waitcnt vmcnt(0)
	ds_write2_b32 v6, v2, v3 offset1:1
	v_add_u32_e32 v2, 0x30c8, v10
	ds_write2_b32 v2, v4, v5 offset1:1
	v_and_b32_e32 v2, -4, v9
	v_mad_u32_u24 v9, v15, s17, v2
	s_waitcnt lgkmcnt(0)
	s_barrier
	ds_read2_b32 v[2:3], v9 offset1:65
	ds_read2_b32 v[4:5], v9 offset0:130 offset1:195
	v_add_u32_e32 v6, 0x400, v9
	v_add_u32_e32 v11, 0x800, v9
	v_add_u32_e32 v9, 0xc00, v9
	s_waitcnt lgkmcnt(1)
	v_cvt_pk_bf16_f32 v2, v2, v3
	s_waitcnt lgkmcnt(0)
	v_cvt_pk_bf16_f32 v3, v4, v5
	ds_read2_b32 v[4:5], v6 offset0:4 offset1:69
	ds_read2_b32 v[6:7], v6 offset0:134 offset1:199
	s_waitcnt lgkmcnt(1)
	v_cvt_pk_bf16_f32 v4, v4, v5
	s_waitcnt lgkmcnt(0)
	v_cvt_pk_bf16_f32 v5, v6, v7
	ds_read2_b32 v[6:7], v11 offset0:8 offset1:73
	s_waitcnt lgkmcnt(0)
	v_cvt_pk_bf16_f32 v10, v6, v7
	ds_read2_b32 v[6:7], v11 offset0:138 offset1:203
	s_waitcnt lgkmcnt(0)
	v_cvt_pk_bf16_f32 v11, v6, v7
	ds_read2_b32 v[6:7], v9 offset0:12 offset1:77
	s_waitcnt lgkmcnt(0)
	v_cvt_pk_bf16_f32 v12, v6, v7
	ds_read2_b32 v[6:7], v9 offset0:142 offset1:207
	v_lshl_add_u32 v9, s16, 6, v14
	s_waitcnt lgkmcnt(0)
	v_cvt_pk_bf16_f32 v13, v6, v7
	v_mov_b64_e32 v[6:7], s[14:15]
	s_movk_i32 s14, 0x300
	v_mad_i64_i32 v[6:7], s[14:15], v9, s14, v[6:7]
	v_lshl_add_u64 v[6:7], v[6:7], 0, s[34:35]
	v_lshl_add_u64 v[6:7], v[6:7], 0, v[182:183]
	global_store_dwordx4 v[6:7], v[2:5], off
	global_store_dwordx4 v[6:7], v[10:13], off offset:16

; DI int get_tid() { int t = threadIdx.x; asm volatile("" : "+v"(t)); return t; }
; DI unsigned pk2(float a, float b) { f32x2_t f = {a, b}; return __builtin_bit_cast(unsigned, __builtin_convertvector(f, bf16x2_t)); }
; DI void tconv_tile(const float* __restrict__ src, long lds, int cvalid, u16* __restrict__ dst, long ldd, int r0, int c0, char* smem) {
;   float (*T)[65] = (float (*)[65])smem;
;   const int tid = get_tid();
;   __syncthreads();
;   const int lr = tid >> 4, lc = (tid & 15) * 4;
; #pragma unroll
;   for (int i = 0; i < 4; ++i) {
;     const int r = lr + 16 * i;
;     float4 v = make_float4(0.f, 0.f, 0.f, 0.f);
;     if (c0 + lc < cvalid) v = *(const float4*)(src + (long)(r0 + r) * lds + c0 + lc);
;     T[r][lc] = v.x; T[r][lc + 1] = v.y; T[r][lc + 2] = v.z; T[r][lc + 3] = v.w;
;   }
;   __syncthreads();
;   const int oc = tid >> 2, seg = (tid & 3) * 16;
;   unsigned pk[8];
; #pragma unroll
;   for (int k = 0; k < 8; ++k) pk[k] = pk2(T[seg + 2 * k][oc], T[seg + 2 * k + 1][oc]);
;   uint4* d = (uint4*)(dst + (long)(c0 + oc) * ldd + r0 + seg);
;   d[0] = make_uint4(pk[0], pk[1], pk[2], pk[3]);
;   d[1] = make_uint4(pk[4], pk[5], pk[6], pk[7]);
; }
; DI void convert_weights(const Params& p, int layer, char* smem) {
;     ...
;       } else if (t < 1856) {
;         const int u = t - 1792, g = u >> 4, v = u & 15;
;         tconv_tile(p.w_pool + (size_t)(e * 4 + g) * 65536, 256, 256, W + WE_POOL + (size_t)g * 65536, 256, (v >> 2) * 64, (v & 3) * 64, smem);
.LBB0_889:
	s_andn2_b64 vcc, exec, s[38:39]
	s_cbranch_vccnz .LBB0_891
	s_add_i32 s11, s4, 0xfffff900
	s_lshr_b32 s12, s11, 4
	s_add_i32 s34, s12, 4
	s_lshl_b64 s[14:15], s[34:35], 18
	v_readlane_b32 s56, v252, 8
	v_readlane_b32 s57, v252, 9
	s_add_u32 s14, s56, s14
	s_mov_b32 s13, s35
	s_addc_u32 s15, s57, s15
	s_lshl_b64 s[12:13], s[12:13], 17
	v_readlane_b32 s11, v252, 43
	s_add_u32 s38, s11, s12
	v_readlane_b32 s11, v252, 44
	s_addc_u32 s39, s11, s13
	s_and_b32 s12, s5, 0xc0
	v_mov_b32_e32 v1, v185
	s_and_b32 s11, s8, 0xc0
	s_lshl_b32 s13, s12, 2
	v_ashrrev_i32_e32 v3, 4, v1
	v_lshlrev_b32_e32 v14, 4, v1
	s_add_u32 s14, s14, s13
	v_add_u32_e32 v10, s11, v3
	v_and_b32_e32 v182, 0xf0, v14
	s_addc_u32 s15, s15, 0
	v_ashrrev_i32_e32 v11, 31, v10
	v_lshl_add_u64 v[8:9], s[14:15], 0, v[182:183]
	v_lshlrev_b64 v[4:5], 10, v[10:11]
	v_lshl_add_u64 v[4:5], v[8:9], 0, v[4:5]
	s_barrier
	global_load_dwordx4 v[100:103], v[4:5], off
	v_add_u32_e32 v104, 16, v10
	v_ashrrev_i32_e32 v105, 31, v104
	v_lshlrev_b64 v[106:107], 10, v[104:105]
	v_lshl_add_u64 v[108:109], v[8:9], 0, v[106:107]
	global_load_dwordx4 v[110:113], v[108:109], off
	v_add_u32_e32 v114, 32, v10
	v_ashrrev_i32_e32 v115, 31, v114
	v_lshlrev_b64 v[116:117], 10, v[114:115]
	v_lshl_add_u64 v[118:119], v[8:9], 0, v[116:117]
	global_load_dwordx4 v[120:123], v[118:119], off
	v_add_u32_e32 v124, 48, v10
	v_ashrrev_i32_e32 v125, 31, v124
	v_lshlrev_b64 v[126:127], 10, v[124:125]
	v_lshl_add_u64 v[128:129], v[8:9], 0, v[126:127]
	global_load_dwordx4 v[130:133], v[128:129], off
	s_nop 0
	s_movk_i32 s13, 0x104
	v_mad_u64_u32 v[12:13], s[14:15], v3, s13, v[182:183]
	v_add_u32_e32 v3, 0x1040, v12
	v_and_b32_e32 v14, 48, v14
	s_lshl_b32 s34, s11, 1
	v_readlane_b32 s64, v252, 16
	v_readlane_b32 s65, v252, 17
	v_readlane_b32 s66, v252, 18
	v_readlane_b32 s67, v252, 19
	v_readlane_b32 s68, v252, 20
	v_readlane_b32 s69, v252, 21
	v_readlane_b32 s70, v252, 22
	v_readlane_b32 s71, v252, 23
	v_lshlrev_b32_e32 v182, 1, v14
	s_mov_b32 s65, 0x2aaaaaab
	s_mov_b64 s[66:67], 0x5a8080
	s_movk_i32 s64, 0x41ff
	s_mov_b64 s[70:71], s[26:27]
	s_mov_b64 s[68:69], s[24:25]
	v_readlane_b32 s58, v252, 10
	v_readlane_b32 s59, v252, 11
	v_readlane_b32 s60, v252, 12
	v_readlane_b32 s61, v252, 13
	v_readlane_b32 s62, v252, 14
	v_readlane_b32 s63, v252, 15
	s_waitcnt vmcnt(3)
	ds_write2_b32 v12, v100, v101 offset1:1
	ds_write2_b32 v12, v102, v103 offset0:2 offset1:3
	s_nop 0
	s_nop 0
	s_nop 0
	s_nop 0
	s_nop 0
	s_waitcnt vmcnt(2)
	ds_write2_b32 v3, v110, v111 offset1:1
	s_nop 0
	s_nop 0
	s_nop 0
	v_add_u32_e32 v3, 0x1048, v12
	s_nop 0
	ds_write2_b32 v3, v112, v113 offset1:1
	s_nop 0
	v_add_u32_e32 v3, 0x2080, v12
	s_waitcnt vmcnt(1)
	ds_write2_b32 v3, v120, v121 offset1:1
	s_nop 0
	s_nop 0
	s_nop 0
	v_add_u32_e32 v3, 0x2088, v12
	s_nop 0
	ds_write2_b32 v3, v122, v123 offset1:1
	s_nop 0
	v_add_u32_e32 v3, 0x30c0, v12
	s_waitcnt vmcnt(0)
	ds_write2_b32 v3, v130, v131 offset1:1
	v_add_u32_e32 v3, 0x30c8, v12
	ds_write2_b32 v3, v132, v133 offset1:1
	v_ashrrev_i32_e32 v3, 2, v1
	v_and_b32_e32 v1, -4, v1
	v_mad_u32_u24 v1, v14, s13, v1
	s_waitcnt lgkmcnt(0)
	v_mov_b32_e32 v4, v130
	v_mov_b32_e32 v5, v131
	v_mov_b32_e32 v6, v132
	v_mov_b32_e32 v7, v133
	s_barrier
	ds_read2_b32 v[4:5], v1 offset1:65
	ds_read2_b32 v[6:7], v1 offset0:130 offset1:195
	v_add_u32_e32 v8, 0x400, v1
	v_add_u32_e32 v10, 0x800, v1
	v_add_u32_e32 v1, 0xc00, v1
	s_waitcnt lgkmcnt(1)
	v_cvt_pk_bf16_f32 v4, v4, v5
	s_waitcnt lgkmcnt(0)
	v_cvt_pk_bf16_f32 v5, v6, v7
	ds_read2_b32 v[6:7], v8 offset0:4 offset1:69
	ds_read2_b32 v[8:9], v8 offset0:134 offset1:199
	ds_read2_b32 v[12:13], v1 offset0:142 offset1:207
	s_waitcnt lgkmcnt(2)
	v_cvt_pk_bf16_f32 v6, v6, v7
	s_waitcnt lgkmcnt(1)
	v_cvt_pk_bf16_f32 v7, v8, v9
	ds_read2_b32 v[8:9], v10 offset0:8 offset1:73
	ds_read2_b32 v[10:11], v10 offset0:138 offset1:203
	s_waitcnt lgkmcnt(1)
	v_cvt_pk_bf16_f32 v8, v8, v9
	s_waitcnt lgkmcnt(0)
	v_cvt_pk_bf16_f32 v9, v10, v11
	ds_read2_b32 v[10:11], v1 offset0:12 offset1:77
	s_waitcnt lgkmcnt(0)
	v_cvt_pk_bf16_f32 v10, v10, v11
	v_cvt_pk_bf16_f32 v11, v12, v13
	v_add_u32_e32 v12, s12, v3
	v_ashrrev_i32_e32 v13, 31, v12
	v_lshlrev_b64 v[12:13], 9, v[12:13]
	v_lshl_add_u64 v[12:13], s[38:39], 0, v[12:13]
	v_lshl_add_u64 v[12:13], v[12:13], 0, s[34:35]
	v_lshl_add_u64 v[12:13], v[12:13], 0, v[182:183]
	global_store_dwordx4 v[12:13], v[4:7], off
	global_store_dwordx4 v[12:13], v[8:11], off offset:16

; DI int get_tid() { int t = threadIdx.x; asm volatile("" : "+v"(t)); return t; }
; DI unsigned pk2(float a, float b) { f32x2_t f = {a, b}; return __builtin_bit_cast(unsigned, __builtin_convertvector(f, bf16x2_t)); }
; DI void tconv_tile(const float* __restrict__ src, long lds, int cvalid, u16* __restrict__ dst, long ldd, int r0, int c0, char* smem) {
;   float (*T)[65] = (float (*)[65])smem;
;   const int tid = get_tid();
;   __syncthreads();
;   const int lr = tid >> 4, lc = (tid & 15) * 4;
; #pragma unroll
;   for (int i = 0; i < 4; ++i) {
;     const int r = lr + 16 * i;
;     float4 v = make_float4(0.f, 0.f, 0.f, 0.f);
;     if (c0 + lc < cvalid) v = *(const float4*)(src + (long)(r0 + r) * lds + c0 + lc);
;     T[r][lc] = v.x; T[r][lc + 1] = v.y; T[r][lc + 2] = v.z; T[r][lc + 3] = v.w;
;   }
;   __syncthreads();
;   const int oc = tid >> 2, seg = (tid & 3) * 16;
;   unsigned pk[8];
; #pragma unroll
;   for (int k = 0; k < 8; ++k) pk[k] = pk2(T[seg + 2 * k][oc], T[seg + 2 * k + 1][oc]);
;   uint4* d = (uint4*)(dst + (long)(c0 + oc) * ldd + r0 + seg);
;   d[0] = make_uint4(pk[0], pk[1], pk[2], pk[3]);
;   d[1] = make_uint4(pk[4], pk[5], pk[6], pk[7]);
; }
; DI void convert_weights(const Params& p, int layer, char* smem) {
;     ...
;       } else if (t < 1792) {
;         const int u = t - 1280;
;         tconv_tile(p.w_out_even + (size_t)e * 2048 * 1024, 1024, 1024, W + WE_OUT, 2048, (u >> 4) * 64, (u & 15) * 64, smem);
.LBB0_892:
	s_andn2_b64 vcc, exec, s[38:39]
	s_cbranch_vccnz .LBB0_894
	s_and_b32 s12, s5, 0x3c0
	v_mov_b32_e32 v1, v185
	s_and_b32 s11, s10, 0x7fffffc0
	s_lshl_b32 s13, s12, 2
	v_ashrrev_i32_e32 v3, 4, v1
	v_readlane_b32 s14, v253, 13
	v_lshlrev_b32_e32 v14, 4, v1
	s_add_u32 s14, s14, s13
	v_readlane_b32 s13, v253, 14
	v_add_u32_e32 v10, s11, v3
	v_and_b32_e32 v182, 0xf0, v14
	s_addc_u32 s15, s13, 0
	v_ashrrev_i32_e32 v11, 31, v10
	v_lshl_add_u64 v[8:9], s[14:15], 0, v[182:183]
	v_lshlrev_b64 v[4:5], 12, v[10:11]
	v_lshl_add_u64 v[4:5], v[8:9], 0, v[4:5]
	s_barrier
	global_load_dwordx4 v[100:103], v[4:5], off
	v_add_u32_e32 v104, 16, v10
	v_ashrrev_i32_e32 v105, 31, v104
	v_lshlrev_b64 v[106:107], 12, v[104:105]
	v_lshl_add_u64 v[108:109], v[8:9], 0, v[106:107]
	global_load_dwordx4 v[110:113], v[108:109], off
	v_add_u32_e32 v114, 32, v10
	v_ashrrev_i32_e32 v115, 31, v114
	v_lshlrev_b64 v[116:117], 12, v[114:115]
	v_lshl_add_u64 v[118:119], v[8:9], 0, v[116:117]
	global_load_dwordx4 v[120:123], v[118:119], off
	v_add_u32_e32 v124, 48, v10
	v_ashrrev_i32_e32 v125, 31, v124
	v_lshlrev_b64 v[126:127], 12, v[124:125]
	v_lshl_add_u64 v[128:129], v[8:9], 0, v[126:127]
	global_load_dwordx4 v[130:133], v[128:129], off
	s_nop 0
	s_movk_i32 s13, 0x104
	v_mad_u64_u32 v[12:13], s[14:15], v3, s13, v[182:183]
	v_add_u32_e32 v3, 0x1040, v12
	v_and_b32_e32 v14, 48, v14
	s_lshl_b32 s34, s11, 1
	v_lshlrev_b32_e32 v182, 1, v14
	s_waitcnt vmcnt(3)
	ds_write2_b32 v12, v100, v101 offset1:1
	ds_write2_b32 v12, v102, v103 offset0:2 offset1:3
	s_nop 0
	s_nop 0
	s_nop 0
	s_nop 0
	s_nop 0
	s_waitcnt vmcnt(2)
	ds_write2_b32 v3, v110, v111 offset1:1
	s_nop 0
	s_nop 0
	s_nop 0
	v_add_u32_e32 v3, 0x1048, v12
	s_nop 0
	ds_write2_b32 v3, v112, v113 offset1:1
	s_nop 0
	v_add_u32_e32 v3, 0x2080, v12
	s_waitcnt vmcnt(1)
	ds_write2_b32 v3, v120, v121 offset1:1
	s_nop 0
	s_nop 0
	s_nop 0
	v_add_u32_e32 v3, 0x2088, v12
	s_nop 0
	ds_write2_b32 v3, v122, v123 offset1:1
	s_nop 0
	v_add_u32_e32 v3, 0x30c0, v12
	s_waitcnt vmcnt(0)
	ds_write2_b32 v3, v130, v131 offset1:1
	v_add_u32_e32 v3, 0x30c8, v12
	ds_write2_b32 v3, v132, v133 offset1:1
	v_ashrrev_i32_e32 v3, 2, v1
	v_and_b32_e32 v1, -4, v1
	v_mad_u32_u24 v1, v14, s13, v1
	s_waitcnt lgkmcnt(0)
	v_mov_b32_e32 v4, v130
	v_mov_b32_e32 v5, v131
	v_mov_b32_e32 v6, v132
	v_mov_b32_e32 v7, v133
	s_barrier
	ds_read2_b32 v[4:5], v1 offset1:65
	ds_read2_b32 v[6:7], v1 offset0:130 offset1:195
	v_add_u32_e32 v8, 0x400, v1
	v_add_u32_e32 v10, 0x800, v1
	v_add_u32_e32 v1, 0xc00, v1
	s_waitcnt lgkmcnt(1)
	v_cvt_pk_bf16_f32 v4, v4, v5
	s_waitcnt lgkmcnt(0)
	v_cvt_pk_bf16_f32 v5, v6, v7
	ds_read2_b32 v[6:7], v8 offset0:4 offset1:69
	ds_read2_b32 v[8:9], v8 offset0:134 offset1:199
	ds_read2_b32 v[12:13], v1 offset0:142 offset1:207
	s_waitcnt lgkmcnt(2)
	v_cvt_pk_bf16_f32 v6, v6, v7
	s_waitcnt lgkmcnt(1)
	v_cvt_pk_bf16_f32 v7, v8, v9
	ds_read2_b32 v[8:9], v10 offset0:8 offset1:73
	ds_read2_b32 v[10:11], v10 offset0:138 offset1:203
	s_waitcnt lgkmcnt(1)
	v_cvt_pk_bf16_f32 v8, v8, v9
	s_waitcnt lgkmcnt(0)
	v_cvt_pk_bf16_f32 v9, v10, v11
	ds_read2_b32 v[10:11], v1 offset0:12 offset1:77
	s_waitcnt lgkmcnt(0)
	v_cvt_pk_bf16_f32 v10, v10, v11
	v_cvt_pk_bf16_f32 v11, v12, v13
	v_add_u32_e32 v12, s12, v3
	v_ashrrev_i32_e32 v13, 31, v12
	v_readlane_b32 s12, v252, 39
	v_lshlrev_b64 v[12:13], 12, v[12:13]
	v_readlane_b32 s13, v252, 40
	s_nop 1
	v_lshl_add_u64 v[12:13], s[12:13], 0, v[12:13]
	v_lshl_add_u64 v[12:13], v[12:13], 0, s[34:35]
	v_lshl_add_u64 v[12:13], v[12:13], 0, v[182:183]
	global_store_dwordx4 v[12:13], v[4:7], off
	global_store_dwordx4 v[12:13], v[8:11], off offset:16

; DI int get_tid() { int t = threadIdx.x; asm volatile("" : "+v"(t)); return t; }
; DI unsigned pk2(float a, float b) { f32x2_t f = {a, b}; return __builtin_bit_cast(unsigned, __builtin_convertvector(f, bf16x2_t)); }
; DI void tconv_tile(const float* __restrict__ src, long lds, int cvalid, u16* __restrict__ dst, long ldd, int r0, int c0, char* smem) {
;   float (*T)[65] = (float (*)[65])smem;
;   const int tid = get_tid();
;   __syncthreads();
;   const int lr = tid >> 4, lc = (tid & 15) * 4;
; #pragma unroll
;   for (int i = 0; i < 4; ++i) {
;     const int r = lr + 16 * i;
;     float4 v = make_float4(0.f, 0.f, 0.f, 0.f);
;     if (c0 + lc < cvalid) v = *(const float4*)(src + (long)(r0 + r) * lds + c0 + lc);
;     T[r][lc] = v.x; T[r][lc + 1] = v.y; T[r][lc + 2] = v.z; T[r][lc + 3] = v.w;
;   }
;   __syncthreads();
;   const int oc = tid >> 2, seg = (tid & 3) * 16;
;   unsigned pk[8];
; #pragma unroll
;   for (int k = 0; k < 8; ++k) pk[k] = pk2(T[seg + 2 * k][oc], T[seg + 2 * k + 1][oc]);
;   uint4* d = (uint4*)(dst + (long)(c0 + oc) * ldd + r0 + seg);
;   d[0] = make_uint4(pk[0], pk[1], pk[2], pk[3]);
;   d[1] = make_uint4(pk[4], pk[5], pk[6], pk[7]);
; }
; DI void convert_weights(const Params& p, int layer, char* smem) {
;     ...
;       if (t < 1280) {
;         tconv_tile(p.w_in_even + (size_t)e * 1024 * 5120, 5120, 5120, W + WE_IN, 1024, (t / 80) * 64, (t % 80) * 64, smem);
.LBB0_895:
	s_andn2_b64 vcc, exec, s[38:39]
	s_cbranch_vccnz .LBB0_884
	s_mul_hi_i32 s11, s4, 0x66666667
	s_lshr_b32 s12, s11, 31
	s_ashr_i32 s11, s11, 5
	s_add_i32 s11, s11, s12
	s_mul_i32 s12, s11, 0xffffec00
	s_add_i32 s12, s5, s12
	s_ashr_i32 s13, s12, 31
	s_lshl_b32 s38, s11, 6
	v_mov_b32_e32 v1, v185
	s_lshl_b64 s[12:13], s[12:13], 2
	v_readlane_b32 s14, v253, 15
	s_add_u32 s12, s14, s12
	v_lshlrev_b32_e32 v12, 4, v1
	v_readlane_b32 s14, v253, 16
	v_ashrrev_i32_e32 v3, 4, v1
	v_and_b32_e32 v182, 0xf0, v12
	s_addc_u32 s13, s14, s13
	v_lshl_add_u64 v[8:9], s[12:13], 0, v[182:183]
	v_add_u32_e32 v13, s38, v3
	s_movk_i32 s15, 0x5000
	v_mad_i64_i32 v[4:5], s[12:13], v13, s15, v[8:9]
	s_barrier
	global_load_dwordx4 v[100:103], v[4:5], off
	s_nop 0
	s_movk_i32 s14, 0x104
	v_mad_u64_u32 v[10:11], s[12:13], v3, s14, v[182:183]
	v_add_u32_e32 v3, 16, v13
	v_and_b32_e32 v14, 48, v12
	s_mulk_i32 s11, 0x1400
	s_ashr_i32 s39, s38, 31
	v_lshlrev_b32_e32 v182, 1, v14
	s_waitcnt vmcnt(0)
	ds_write2_b32 v10, v100, v101 offset1:1
	ds_write2_b32 v10, v102, v103 offset0:2 offset1:3
	v_mad_i64_i32 v[4:5], s[12:13], v3, s15, v[8:9]
	global_load_dwordx4 v[4:7], v[4:5], off
	v_add_u32_e32 v3, 0x1040, v10
	s_waitcnt vmcnt(0)
	ds_write2_b32 v3, v4, v5 offset1:1
	v_add_u32_e32 v3, 0x1048, v10
	ds_write2_b32 v3, v6, v7 offset1:1
	v_add_u32_e32 v3, 32, v13
	v_mad_i64_i32 v[4:5], s[12:13], v3, s15, v[8:9]
	global_load_dwordx4 v[4:7], v[4:5], off
	v_add_u32_e32 v3, 0x2080, v10
	s_waitcnt vmcnt(0)
	ds_write2_b32 v3, v4, v5 offset1:1
	v_add_u32_e32 v3, 0x2088, v10
	ds_write2_b32 v3, v6, v7 offset1:1
	v_add_u32_e32 v3, 48, v13
	v_mad_i64_i32 v[4:5], s[12:13], v3, s15, v[8:9]
	global_load_dwordx4 v[4:7], v[4:5], off
	v_add_u32_e32 v3, 0x30c0, v10
	s_waitcnt vmcnt(0)
	ds_write2_b32 v3, v4, v5 offset1:1
	v_add_u32_e32 v3, 0x30c8, v10
	ds_write2_b32 v3, v6, v7 offset1:1
	v_ashrrev_i32_e32 v3, 2, v1
	v_and_b32_e32 v1, -4, v1
	v_mad_u32_u24 v1, v14, s14, v1
	s_waitcnt lgkmcnt(0)
	s_barrier
	ds_read2_b32 v[4:5], v1 offset1:65
	ds_read2_b32 v[6:7], v1 offset0:130 offset1:195
	v_add_u32_e32 v8, 0x400, v1
	v_add_u32_e32 v10, 0x800, v1
	v_add_u32_e32 v1, 0xc00, v1
	s_waitcnt lgkmcnt(1)
	v_cvt_pk_bf16_f32 v4, v4, v5
	s_waitcnt lgkmcnt(0)
	v_cvt_pk_bf16_f32 v5, v6, v7
	ds_read2_b32 v[6:7], v8 offset0:4 offset1:69
	ds_read2_b32 v[8:9], v8 offset0:134 offset1:199
	ds_read2_b32 v[12:13], v1 offset0:142 offset1:207
	v_readlane_b32 s12, v255, 5
	v_readlane_b32 s16, v255, 9
	s_waitcnt lgkmcnt(2)
	v_cvt_pk_bf16_f32 v6, v6, v7
	s_waitcnt lgkmcnt(1)
	v_cvt_pk_bf16_f32 v7, v8, v9
	ds_read2_b32 v[8:9], v10 offset0:8 offset1:73
	ds_read2_b32 v[10:11], v10 offset0:138 offset1:203
	v_readlane_b32 s17, v255, 10
	v_readlane_b32 s13, v255, 6
	v_readlane_b32 s14, v255, 7
	s_waitcnt lgkmcnt(1)
	v_cvt_pk_bf16_f32 v8, v8, v9
	s_waitcnt lgkmcnt(0)
	v_cvt_pk_bf16_f32 v9, v10, v11
	ds_read2_b32 v[10:11], v1 offset0:12 offset1:77
	v_subrev_u32_e32 v1, s11, v3
	v_readlane_b32 s15, v255, 8
	v_readlane_b32 s18, v255, 11
	v_readlane_b32 s19, v255, 12
	s_waitcnt lgkmcnt(0)
	v_cvt_pk_bf16_f32 v10, v10, v11
	v_cvt_pk_bf16_f32 v11, v12, v13
	v_add_u32_e32 v12, s5, v1
	v_ashrrev_i32_e32 v13, 31, v12
	v_lshlrev_b64 v[12:13], 11, v[12:13]
	v_lshl_add_u64 v[12:13], s[16:17], 0, v[12:13]
	v_lshl_add_u64 v[12:13], s[38:39], 1, v[12:13]
	v_lshl_add_u64 v[12:13], v[12:13], 0, v[182:183]
	global_store_dwordx4 v[12:13], v[4:7], off
	global_store_dwordx4 v[12:13], v[8:11], off offset:16
	s_branch .LBB0_884

; DI int get_tid() { int t = threadIdx.x; asm volatile("" : "+v"(t)); return t; }
; DI unsigned pk2(float a, float b) { f32x2_t f = {a, b}; return __builtin_bit_cast(unsigned, __builtin_convertvector(f, bf16x2_t)); }
; DI void tconv_tile(const float* __restrict__ src, long lds, int cvalid, u16* __restrict__ dst, long ldd, int r0, int c0, char* smem) {
;   float (*T)[65] = (float (*)[65])smem;
;   const int tid = get_tid();
;   __syncthreads();
;   const int lr = tid >> 4, lc = (tid & 15) * 4;
; #pragma unroll
;   for (int i = 0; i < 4; ++i) {
;     const int r = lr + 16 * i;
;     float4 v = make_float4(0.f, 0.f, 0.f, 0.f);
;     if (c0 + lc < cvalid) v = *(const float4*)(src + (long)(r0 + r) * lds + c0 + lc);
;     T[r][lc] = v.x; T[r][lc + 1] = v.y; T[r][lc + 2] = v.z; T[r][lc + 3] = v.w;
;   }
;   __syncthreads();
;   const int oc = tid >> 2, seg = (tid & 3) * 16;
;   unsigned pk[8];
; #pragma unroll
;   for (int k = 0; k < 8; ++k) pk[k] = pk2(T[seg + 2 * k][oc], T[seg + 2 * k + 1][oc]);
;   uint4* d = (uint4*)(dst + (long)(c0 + oc) * ldd + r0 + seg);
;   d[0] = make_uint4(pk[0], pk[1], pk[2], pk[3]);
;   d[1] = make_uint4(pk[4], pk[5], pk[6], pk[7]);
; }
; DI void convert_weights(const Params& p, int layer, char* smem) {
;     ...
;       } else if (t < 976) {
;         const int u = t - 720;
;         tconv_tile(p.w_o + (size_t)o * 1024 * 1024, 1024, 1024, W + WO_O, 1024, (u >> 4) * 64, (u & 15) * 64, smem);
.LBB0_1285:
	s_and_b64 vcc, exec, s[38:39]
	s_cbranch_vccz .LBB0_1287
	s_and_b32 s14, s5, 0x3c0
	v_mov_b32_e32 v7, v185
	s_and_b32 s13, s8, 0x7fffffc0
	s_lshl_b32 s15, s14, 2
	v_ashrrev_i32_e32 v2, 4, v7
	v_readlane_b32 s16, v255, 5
	v_lshlrev_b32_e32 v11, 4, v7
	v_readlane_b32 s17, v255, 6
	s_add_u32 s16, s16, s15
	v_add_u32_e32 v8, s13, v2
	v_and_b32_e32 v182, 0xf0, v11
	s_addc_u32 s17, s17, 0
	v_ashrrev_i32_e32 v9, 31, v8
	v_lshl_add_u64 v[4:5], s[16:17], 0, v[182:183]
	v_lshlrev_b64 v[0:1], 12, v[8:9]
	v_lshl_add_u64 v[0:1], v[4:5], 0, v[0:1]
	s_movk_i32 s15, 0x104
	s_waitcnt lgkmcnt(0)
	s_barrier
	global_load_dwordx4 v[102:105], v[0:1], off
	v_add_u32_e32 v106, 16, v8
	v_ashrrev_i32_e32 v107, 31, v106
	v_lshlrev_b64 v[108:109], 12, v[106:107]
	v_lshl_add_u64 v[110:111], v[4:5], 0, v[108:109]
	global_load_dwordx4 v[178:181], v[110:111], off
	v_add_u32_e32 v112, 32, v8
	v_ashrrev_i32_e32 v186, 31, v112
	v_mov_b32_e32 v232, v112
	v_mov_b32_e32 v233, v186
	v_lshlrev_b64 v[188:189], 12, v[232:233]
	v_lshl_add_u64 v[190:191], v[4:5], 0, v[188:189]
	global_load_dwordx4 v[192:195], v[190:191], off
	v_add_u32_e32 v187, 48, v8
	v_ashrrev_i32_e32 v196, 31, v187
	v_mov_b32_e32 v234, v187
	v_mov_b32_e32 v235, v196
	v_lshlrev_b64 v[224:225], 12, v[234:235]
	v_lshl_add_u64 v[226:227], v[4:5], 0, v[224:225]
	global_load_dwordx4 v[228:231], v[226:227], off
	v_mad_u64_u32 v[12:13], s[16:17], v2, s15, v[182:183]
	s_nop 0
	v_add_u32_e32 v9, 0x1040, v12
	s_lshl_b32 s34, s13, 1
	v_readlane_b32 s18, v255, 7
	v_readlane_b32 s19, v255, 8
	v_readlane_b32 s20, v255, 9
	v_readlane_b32 s21, v255, 10
	v_readlane_b32 s22, v255, 11
	v_readlane_b32 s23, v255, 12
	s_waitcnt vmcnt(3)
	ds_write2_b32 v12, v102, v103 offset1:1
	ds_write2_b32 v12, v104, v105 offset0:2 offset1:3
	s_nop 0
	s_nop 0
	s_nop 0
	s_nop 0
	s_nop 0
	s_waitcnt vmcnt(2)
	ds_write2_b32 v9, v178, v179 offset1:1
	v_add_u32_e32 v0, 0x1048, v12
	ds_write2_b32 v0, v180, v181 offset1:1
	s_nop 0
	s_nop 0
	s_nop 0
	s_nop 0
	s_nop 0
	v_add_u32_e32 v9, 0x2080, v12
	s_waitcnt vmcnt(1)
	ds_write2_b32 v9, v192, v193 offset1:1
	v_add_u32_e32 v0, 0x2088, v12
	ds_write2_b32 v0, v194, v195 offset1:1
	s_nop 0
	s_nop 0
	s_nop 0
	s_nop 0
	s_nop 0
	v_add_u32_e32 v4, 0x30c0, v12
	v_and_b32_e32 v9, 48, v11
	v_ashrrev_i32_e32 v8, 2, v7
	v_lshlrev_b32_e32 v182, 1, v9
	s_waitcnt vmcnt(0)
	ds_write2_b32 v4, v228, v229 offset1:1
	v_add_u32_e32 v0, 0x30c8, v12
	ds_write2_b32 v0, v230, v231 offset1:1
	v_and_b32_e32 v0, -4, v7
	v_mad_u32_u24 v7, v9, s15, v0
	s_waitcnt lgkmcnt(0)
	v_mov_b32_e32 v1, v229
	v_mov_b32_e32 v2, v230
	v_mov_b32_e32 v3, v231
	s_barrier
	ds_read2_b32 v[0:1], v7 offset1:65
	ds_read2_b32 v[2:3], v7 offset0:130 offset1:195
	v_add_u32_e32 v4, 0x400, v7
	v_add_u32_e32 v11, 0x800, v7
	v_add_u32_e32 v7, 0xc00, v7
	s_waitcnt lgkmcnt(1)
	v_cvt_pk_bf16_f32 v0, v0, v1
	s_waitcnt lgkmcnt(0)
	v_cvt_pk_bf16_f32 v1, v2, v3
	ds_read2_b32 v[2:3], v4 offset0:4 offset1:69
	ds_read2_b32 v[4:5], v4 offset0:134 offset1:199
	s_waitcnt lgkmcnt(1)
	v_cvt_pk_bf16_f32 v2, v2, v3
	s_waitcnt lgkmcnt(0)
	v_cvt_pk_bf16_f32 v3, v4, v5
	ds_read2_b32 v[4:5], v11 offset0:8 offset1:73
	s_waitcnt lgkmcnt(0)
	v_cvt_pk_bf16_f32 v12, v4, v5
	ds_read2_b32 v[4:5], v11 offset0:138 offset1:203
	s_waitcnt lgkmcnt(0)
	v_cvt_pk_bf16_f32 v13, v4, v5
	ds_read2_b32 v[4:5], v7 offset0:12 offset1:77
	s_waitcnt lgkmcnt(0)
	v_cvt_pk_bf16_f32 v14, v4, v5
	ds_read2_b32 v[4:5], v7 offset0:142 offset1:207
	s_waitcnt lgkmcnt(0)
	v_cvt_pk_bf16_f32 v15, v4, v5
	v_add_u32_e32 v4, s14, v8
	v_ashrrev_i32_e32 v5, 31, v4
	v_readlane_b32 s14, v252, 26
	v_lshlrev_b64 v[4:5], 11, v[4:5]
	v_readlane_b32 s15, v252, 27
	s_nop 1
	v_lshl_add_u64 v[4:5], s[14:15], 0, v[4:5]
	v_lshl_add_u64 v[4:5], v[4:5], 0, s[34:35]
	v_lshl_add_u64 v[4:5], v[4:5], 0, v[182:183]
	global_store_dwordx4 v[4:5], v[0:3], off
	global_store_dwordx4 v[4:5], v[12:15], off offset:16

; DI unsigned pk2(float a, float b) { f32x2_t f = {a, b}; return __builtin_bit_cast(unsigned, __builtin_convertvector(f, bf16x2_t)); }
; DI void tconv_tile(const float* __restrict__ src, long lds, int cvalid, u16* __restrict__ dst, long ldd, int r0, int c0, char* smem) {
;     ...
;   __syncthreads();
;   const int lr = tid >> 4, lc = (tid & 15) * 4;
; #pragma unroll
;   for (int i = 0; i < 4; ++i) {
;     const int r = lr + 16 * i;
;     float4 v = make_float4(0.f, 0.f, 0.f, 0.f);
;     if (c0 + lc < cvalid) v = *(const float4*)(src + (long)(r0 + r) * lds + c0 + lc);
;     T[r][lc] = v.x; T[r][lc + 1] = v.y; T[r][lc + 2] = v.z; T[r][lc + 3] = v.w;
;   }
;   __syncthreads();
;   const int oc = tid >> 2, seg = (tid & 3) * 16;
;   unsigned pk[8];
; #pragma unroll
;   for (int k = 0; k < 8; ++k) pk[k] = pk2(T[seg + 2 * k][oc], T[seg + 2 * k + 1][oc]);
;   uint4* d = (uint4*)(dst + (long)(c0 + oc) * ldd + r0 + seg);
;   d[0] = make_uint4(pk[0], pk[1], pk[2], pk[3]);
;   d[1] = make_uint4(pk[4], pk[5], pk[6], pk[7]);
; DI void convert_weights(const Params& p, int layer, char* smem) {
;     ...
;       } else if (t < 720) {
;         const int u = t - 592;
;         const int c0 = (u & 31) * 64, hh = c0 >> 8, j0 = c0 & 255;
;         const int drow0 = j0 < 128 ? hh * 128 + j0 : 1024 + hh * 128 + (j0 - 128);
;         tconv_tile(p.w_kv_up + (size_t)o * 256 * 2048, 2048, 2048, W + WO_KV + (long)(drow0 - c0) * 256, 256, (u >> 5) * 64, c0, smem);
.LBB0_1288:
	s_andn2_b64 vcc, exec, s[38:39]
	s_cbranch_vccnz .LBB0_1290
	s_add_i32 s13, s5, 0xffff6c00
	s_and_b32 s14, s13, 0x7c0
	s_and_b32 s13, s13, 0xc0
	s_and_b32 s15, s11, 0x380
	s_or_b32 s16, s15, s13
	s_add_i32 s15, s13, s15
	s_addk_i32 s15, 0x380
	s_cmpk_lt_u32 s13, 0x80
	s_cselect_b32 s13, s16, s15
	s_sub_i32 s16, s13, s14
	s_ashr_i32 s17, s16, 31
	s_lshl_b64 s[16:17], s[16:17], 9
	s_add_u32 s38, s87, s16
	v_mov_b32_e32 v7, v185
	v_readlane_b32 s40, v252, 0
	s_addc_u32 s39, s90, s17
	s_and_b32 s13, s9, 0x7fffffc0
	s_lshl_b32 s15, s14, 2
	v_ashrrev_i32_e32 v2, 4, v7
	v_readlane_b32 s46, v252, 6
	v_lshlrev_b32_e32 v11, 4, v7
	v_readlane_b32 s47, v252, 7
	s_add_u32 s16, s46, s15
	v_add_u32_e32 v8, s13, v2
	v_and_b32_e32 v182, 0xf0, v11
	s_addc_u32 s17, s47, 0
	v_ashrrev_i32_e32 v9, 31, v8
	v_lshl_add_u64 v[4:5], s[16:17], 0, v[182:183]
	v_lshlrev_b64 v[0:1], 13, v[8:9]
	v_lshl_add_u64 v[0:1], v[4:5], 0, v[0:1]
	s_movk_i32 s15, 0x104
	s_waitcnt lgkmcnt(0)
	s_barrier
	global_load_dwordx4 v[102:105], v[0:1], off
	v_add_u32_e32 v106, 16, v8
	v_ashrrev_i32_e32 v107, 31, v106
	v_lshlrev_b64 v[108:109], 13, v[106:107]
	v_lshl_add_u64 v[110:111], v[4:5], 0, v[108:109]
	global_load_dwordx4 v[178:181], v[110:111], off
	v_add_u32_e32 v112, 32, v8
	v_ashrrev_i32_e32 v186, 31, v112
	v_mov_b32_e32 v232, v112
	v_mov_b32_e32 v233, v186
	v_lshlrev_b64 v[188:189], 13, v[232:233]
	v_lshl_add_u64 v[190:191], v[4:5], 0, v[188:189]
	global_load_dwordx4 v[192:195], v[190:191], off
	v_add_u32_e32 v187, 48, v8
	v_ashrrev_i32_e32 v196, 31, v187
	v_mov_b32_e32 v234, v187
	v_mov_b32_e32 v235, v196
	v_lshlrev_b64 v[224:225], 13, v[234:235]
	v_lshl_add_u64 v[226:227], v[4:5], 0, v[224:225]
	global_load_dwordx4 v[228:231], v[226:227], off
	v_mad_u64_u32 v[12:13], s[16:17], v2, s15, v[182:183]
	s_nop 0
	v_add_u32_e32 v9, 0x1040, v12
	s_lshl_b32 s34, s13, 1
	v_readlane_b32 s41, v252, 1
	v_readlane_b32 s42, v252, 2
	v_readlane_b32 s43, v252, 3
	v_readlane_b32 s44, v252, 4
	v_readlane_b32 s45, v252, 5
	s_waitcnt vmcnt(3)
	ds_write2_b32 v12, v102, v103 offset1:1
	ds_write2_b32 v12, v104, v105 offset0:2 offset1:3
	s_nop 0
	s_nop 0
	s_nop 0
	s_nop 0
	s_nop 0
	s_waitcnt vmcnt(2)
	ds_write2_b32 v9, v178, v179 offset1:1
	v_add_u32_e32 v0, 0x1048, v12
	ds_write2_b32 v0, v180, v181 offset1:1
	s_nop 0
	s_nop 0
	s_nop 0
	s_nop 0
	s_nop 0
	v_add_u32_e32 v9, 0x2080, v12
	s_waitcnt vmcnt(1)
	ds_write2_b32 v9, v192, v193 offset1:1
	v_add_u32_e32 v0, 0x2088, v12
	ds_write2_b32 v0, v194, v195 offset1:1
	s_nop 0
	s_nop 0
	s_nop 0
	s_nop 0
	s_nop 0
	v_add_u32_e32 v4, 0x30c0, v12
	v_and_b32_e32 v9, 48, v11
	v_ashrrev_i32_e32 v8, 2, v7
	v_lshlrev_b32_e32 v182, 1, v9
	s_waitcnt vmcnt(0)
	ds_write2_b32 v4, v228, v229 offset1:1
	v_add_u32_e32 v0, 0x30c8, v12
	ds_write2_b32 v0, v230, v231 offset1:1
	v_and_b32_e32 v0, -4, v7
	v_mad_u32_u24 v7, v9, s15, v0
	s_waitcnt lgkmcnt(0)
	v_mov_b32_e32 v1, v229
	v_mov_b32_e32 v2, v230
	v_mov_b32_e32 v3, v231
	s_barrier
	ds_read2_b32 v[0:1], v7 offset1:65
	ds_read2_b32 v[2:3], v7 offset0:130 offset1:195
	v_add_u32_e32 v4, 0x400, v7
	v_add_u32_e32 v11, 0x800, v7
	v_add_u32_e32 v7, 0xc00, v7
	s_waitcnt lgkmcnt(1)
	v_cvt_pk_bf16_f32 v0, v0, v1
	s_waitcnt lgkmcnt(0)
	v_cvt_pk_bf16_f32 v1, v2, v3
	ds_read2_b32 v[2:3], v4 offset0:4 offset1:69
	ds_read2_b32 v[4:5], v4 offset0:134 offset1:199
	s_waitcnt lgkmcnt(1)
	v_cvt_pk_bf16_f32 v2, v2, v3
	s_waitcnt lgkmcnt(0)
	v_cvt_pk_bf16_f32 v3, v4, v5
	ds_read2_b32 v[4:5], v11 offset0:8 offset1:73
	s_waitcnt lgkmcnt(0)
	v_cvt_pk_bf16_f32 v12, v4, v5
	ds_read2_b32 v[4:5], v11 offset0:138 offset1:203
	s_waitcnt lgkmcnt(0)
	v_cvt_pk_bf16_f32 v13, v4, v5
	ds_read2_b32 v[4:5], v7 offset0:12 offset1:77
	s_waitcnt lgkmcnt(0)
	v_cvt_pk_bf16_f32 v14, v4, v5
	ds_read2_b32 v[4:5], v7 offset0:142 offset1:207
	s_waitcnt lgkmcnt(0)
	v_cvt_pk_bf16_f32 v15, v4, v5
	v_add_u32_e32 v4, s14, v8
	v_ashrrev_i32_e32 v5, 31, v4
	v_lshlrev_b64 v[4:5], 9, v[4:5]
	v_lshl_add_u64 v[4:5], s[38:39], 0, v[4:5]
	v_lshl_add_u64 v[4:5], v[4:5], 0, s[34:35]
	v_lshl_add_u64 v[4:5], v[4:5], 0, v[182:183]
	global_store_dwordx4 v[4:5], v[0:3], off
	global_store_dwordx4 v[4:5], v[12:15], off offset:16

; DI unsigned pk2(float a, float b) { f32x2_t f = {a, b}; return __builtin_bit_cast(unsigned, __builtin_convertvector(f, bf16x2_t)); }
; DI void tconv_tile(const float* __restrict__ src, long lds, int cvalid, u16* __restrict__ dst, long ldd, int r0, int c0, char* smem) {
;     ...
;   __syncthreads();
;   const int lr = tid >> 4, lc = (tid & 15) * 4;
; #pragma unroll
;   for (int i = 0; i < 4; ++i) {
;     const int r = lr + 16 * i;
;     float4 v = make_float4(0.f, 0.f, 0.f, 0.f);
;     if (c0 + lc < cvalid) v = *(const float4*)(src + (long)(r0 + r) * lds + c0 + lc);
;     T[r][lc] = v.x; T[r][lc + 1] = v.y; T[r][lc + 2] = v.z; T[r][lc + 3] = v.w;
;   }
;   __syncthreads();
;   const int oc = tid >> 2, seg = (tid & 3) * 16;
;   unsigned pk[8];
; #pragma unroll
;   for (int k = 0; k < 8; ++k) pk[k] = pk2(T[seg + 2 * k][oc], T[seg + 2 * k + 1][oc]);
;   uint4* d = (uint4*)(dst + (long)(c0 + oc) * ldd + r0 + seg);
;   d[0] = make_uint4(pk[0], pk[1], pk[2], pk[3]);
;   d[1] = make_uint4(pk[4], pk[5], pk[6], pk[7]);
; DI void convert_weights(const Params& p, int layer, char* smem) {
;     ...
;       } else if (t < 592) {
;         const int u = t - 448;
;         tconv_tile(p.w_q_up + (size_t)o * 384 * 1536, 1536, 1536, W + WO_Q, 384, (u / 24) * 64, (u % 24) * 64, smem);
.LBB0_1291:
	s_andn2_b64 vcc, exec, s[38:39]
	s_cbranch_vccnz .LBB0_1293
	s_add_i32 s14, s4, 64
	s_and_b32 s13, s14, 0xff
	s_mulk_i32 s13, 0xab
	s_bfe_u32 s13, s13, 0x4000c
	s_mul_i32 s15, s13, 24
	s_sub_i32 s14, s14, s15
	s_and_b32 s16, s14, 0xff
	v_readlane_b32 s40, v252, 0
	v_mov_b32_e32 v7, v185
	s_lshl_b32 s14, s16, 8
	v_readlane_b32 s44, v252, 4
	v_readlane_b32 s45, v252, 5
	v_lshlrev_b32_e32 v11, 4, v7
	s_add_u32 s14, s44, s14
	v_ashrrev_i32_e32 v2, 4, v7
	v_and_b32_e32 v182, 0xf0, v11
	s_addc_u32 s15, s45, 0
	v_lshl_add_u64 v[4:5], s[14:15], 0, v[182:183]
	v_lshl_add_u32 v12, s13, 6, v2
	s_movk_i32 s18, 0x1800
	v_mad_i64_i32 v[0:1], s[14:15], v12, s18, v[4:5]
	s_movk_i32 s17, 0x104
	s_waitcnt lgkmcnt(0)
	s_barrier
	global_load_dwordx4 v[102:105], v[0:1], off
	v_mad_u64_u32 v[8:9], s[14:15], v2, s17, v[182:183]
	s_nop 0
	v_add_u32_e32 v9, 0x1040, v8
	s_lshl_b32 s34, s13, 7
	v_readlane_b32 s41, v252, 1
	v_readlane_b32 s42, v252, 2
	v_readlane_b32 s43, v252, 3
	v_readlane_b32 s46, v252, 6
	v_readlane_b32 s47, v252, 7
	s_waitcnt vmcnt(0)
	ds_write2_b32 v8, v102, v103 offset1:1
	ds_write2_b32 v8, v104, v105 offset0:2 offset1:3
	v_add_u32_e32 v0, 16, v12
	v_mad_i64_i32 v[0:1], s[14:15], v0, s18, v[4:5]
	global_load_dwordx4 v[0:3], v[0:1], off
	s_waitcnt vmcnt(0)
	ds_write2_b32 v9, v0, v1 offset1:1
	v_add_u32_e32 v0, 0x1048, v8
	ds_write2_b32 v0, v2, v3 offset1:1
	v_add_u32_e32 v0, 32, v12
	v_mad_i64_i32 v[0:1], s[14:15], v0, s18, v[4:5]
	global_load_dwordx4 v[0:3], v[0:1], off
	v_add_u32_e32 v9, 0x2080, v8
	s_waitcnt vmcnt(0)
	ds_write2_b32 v9, v0, v1 offset1:1
	v_add_u32_e32 v0, 0x2088, v8
	ds_write2_b32 v0, v2, v3 offset1:1
	v_add_u32_e32 v0, 48, v12
	v_mad_i64_i32 v[0:1], s[14:15], v0, s18, v[4:5]
	global_load_dwordx4 v[0:3], v[0:1], off
	v_add_u32_e32 v4, 0x30c0, v8
	v_and_b32_e32 v9, 48, v11
	v_readlane_b32 s14, v252, 29
	v_readlane_b32 s15, v252, 30
	v_lshlrev_b32_e32 v182, 1, v9
	s_waitcnt vmcnt(0)
	ds_write2_b32 v4, v0, v1 offset1:1
	v_add_u32_e32 v0, 0x30c8, v8
	ds_write2_b32 v0, v2, v3 offset1:1
	v_and_b32_e32 v0, -4, v7
	v_ashrrev_i32_e32 v8, 2, v7
	v_mad_u32_u24 v7, v9, s17, v0
	s_waitcnt lgkmcnt(0)
	s_barrier
	ds_read2_b32 v[0:1], v7 offset1:65
	ds_read2_b32 v[2:3], v7 offset0:130 offset1:195
	v_add_u32_e32 v4, 0x400, v7
	v_add_u32_e32 v11, 0x800, v7
	v_add_u32_e32 v7, 0xc00, v7
	s_waitcnt lgkmcnt(1)
	v_cvt_pk_bf16_f32 v0, v0, v1
	s_waitcnt lgkmcnt(0)
	v_cvt_pk_bf16_f32 v1, v2, v3
	ds_read2_b32 v[2:3], v4 offset0:4 offset1:69
	ds_read2_b32 v[4:5], v4 offset0:134 offset1:199
	s_waitcnt lgkmcnt(1)
	v_cvt_pk_bf16_f32 v2, v2, v3
	s_waitcnt lgkmcnt(0)
	v_cvt_pk_bf16_f32 v3, v4, v5
	ds_read2_b32 v[4:5], v11 offset0:8 offset1:73
	s_waitcnt lgkmcnt(0)
	v_cvt_pk_bf16_f32 v12, v4, v5
	ds_read2_b32 v[4:5], v11 offset0:138 offset1:203
	s_waitcnt lgkmcnt(0)
	v_cvt_pk_bf16_f32 v13, v4, v5
	ds_read2_b32 v[4:5], v7 offset0:12 offset1:77
	s_waitcnt lgkmcnt(0)
	v_cvt_pk_bf16_f32 v14, v4, v5
	ds_read2_b32 v[4:5], v7 offset0:142 offset1:207
	v_lshl_add_u32 v7, s16, 6, v8
	s_waitcnt lgkmcnt(0)
	v_cvt_pk_bf16_f32 v15, v4, v5
	v_mov_b64_e32 v[4:5], s[14:15]
	s_movk_i32 s14, 0x300
	v_mad_i64_i32 v[4:5], s[14:15], v7, s14, v[4:5]
	v_lshl_add_u64 v[4:5], v[4:5], 0, s[34:35]
	v_lshl_add_u64 v[4:5], v[4:5], 0, v[182:183]
	global_store_dwordx4 v[4:5], v[0:3], off
	global_store_dwordx4 v[4:5], v[12:15], off offset:16

; DI unsigned pk2(float a, float b) { f32x2_t f = {a, b}; return __builtin_bit_cast(unsigned, __builtin_convertvector(f, bf16x2_t)); }
; DI void tconv_tile(const float* __restrict__ src, long lds, int cvalid, u16* __restrict__ dst, long ldd, int r0, int c0, char* smem) {
;     ...
;   __syncthreads();
;   const int lr = tid >> 4, lc = (tid & 15) * 4;
; #pragma unroll
;   for (int i = 0; i < 4; ++i) {
;     const int r = lr + 16 * i;
;     float4 v = make_float4(0.f, 0.f, 0.f, 0.f);
;     if (c0 + lc < cvalid) v = *(const float4*)(src + (long)(r0 + r) * lds + c0 + lc);
;     T[r][lc] = v.x; T[r][lc + 1] = v.y; T[r][lc + 2] = v.z; T[r][lc + 3] = v.w;
;   }
;   __syncthreads();
;   const int oc = tid >> 2, seg = (tid & 3) * 16;
;   unsigned pk[8];
; #pragma unroll
;   for (int k = 0; k < 8; ++k) pk[k] = pk2(T[seg + 2 * k][oc], T[seg + 2 * k + 1][oc]);
;   uint4* d = (uint4*)(dst + (long)(c0 + oc) * ldd + r0 + seg);
;   d[0] = make_uint4(pk[0], pk[1], pk[2], pk[3]);
;   d[1] = make_uint4(pk[4], pk[5], pk[6], pk[7]);
; DI void convert_weights(const Params& p, int layer, char* smem) {
;     ...
;       } else if (t < 1856) {
;         const int u = t - 1792, g = u >> 4, v = u & 15;
;         tconv_tile(p.w_pool + (size_t)(e * 4 + g) * 65536, 256, 256, W + WE_POOL + (size_t)g * 65536, 256, (v >> 2) * 64, (v & 3) * 64, smem);
.LBB0_1771:
	s_andn2_b64 vcc, exec, s[38:39]
	s_cbranch_vccnz .LBB0_1773
	s_add_i32 s11, s4, 0xfffff900
	s_lshr_b32 s34, s11, 4
	s_lshl_b64 s[12:13], s[34:35], 18
	v_readlane_b32 s56, v252, 8
	v_readlane_b32 s57, v252, 9
	s_add_u32 s14, s56, s12
	s_addc_u32 s15, s57, s13
	s_lshl_b64 s[12:13], s[34:35], 17
	v_readlane_b32 s11, v252, 43
	s_add_u32 s38, s11, s12
	v_readlane_b32 s11, v252, 44
	s_addc_u32 s39, s11, s13
	s_and_b32 s12, s5, 0xc0
	v_mov_b32_e32 v1, v185
	s_and_b32 s11, s8, 0xc0
	s_lshl_b32 s13, s12, 2
	v_ashrrev_i32_e32 v3, 4, v1
	v_lshlrev_b32_e32 v14, 4, v1
	s_add_u32 s14, s14, s13
	v_add_u32_e32 v10, s11, v3
	v_and_b32_e32 v182, 0xf0, v14
	s_addc_u32 s15, s15, 0
	v_ashrrev_i32_e32 v11, 31, v10
	v_lshl_add_u64 v[8:9], s[14:15], 0, v[182:183]
	v_lshlrev_b64 v[4:5], 10, v[10:11]
	v_lshl_add_u64 v[4:5], v[8:9], 0, v[4:5]
	s_waitcnt lgkmcnt(0)
	s_barrier
	global_load_dwordx4 v[100:103], v[4:5], off
	v_add_u32_e32 v104, 16, v10
	v_ashrrev_i32_e32 v105, 31, v104
	v_lshlrev_b64 v[106:107], 10, v[104:105]
	v_lshl_add_u64 v[108:109], v[8:9], 0, v[106:107]
	global_load_dwordx4 v[110:113], v[108:109], off
	v_add_u32_e32 v114, 32, v10
	v_ashrrev_i32_e32 v115, 31, v114
	v_lshlrev_b64 v[116:117], 10, v[114:115]
	v_lshl_add_u64 v[118:119], v[8:9], 0, v[116:117]
	global_load_dwordx4 v[120:123], v[118:119], off
	v_add_u32_e32 v124, 48, v10
	v_ashrrev_i32_e32 v125, 31, v124
	v_lshlrev_b64 v[126:127], 10, v[124:125]
	v_lshl_add_u64 v[128:129], v[8:9], 0, v[126:127]
	global_load_dwordx4 v[154:157], v[128:129], off
	s_nop 0
	s_movk_i32 s13, 0x104
	v_mad_u64_u32 v[12:13], s[14:15], v3, s13, v[182:183]
	v_add_u32_e32 v3, 0x1040, v12
	v_and_b32_e32 v14, 48, v14
	s_lshl_b32 s34, s11, 1
	v_readlane_b32 s64, v252, 16
	v_readlane_b32 s65, v252, 17
	v_readlane_b32 s66, v252, 18
	v_readlane_b32 s67, v252, 19
	v_readlane_b32 s68, v252, 20
	v_readlane_b32 s69, v252, 21
	v_readlane_b32 s70, v252, 22
	v_readlane_b32 s71, v252, 23
	v_lshlrev_b32_e32 v182, 1, v14
	s_mov_b32 s65, 0x2aaaaaab
	s_mov_b64 s[66:67], 0x5a8080
	s_movk_i32 s64, 0x41ff
	s_mov_b64 s[70:71], s[26:27]
	s_mov_b64 s[68:69], s[24:25]
	v_readlane_b32 s58, v252, 10
	v_readlane_b32 s59, v252, 11
	v_readlane_b32 s60, v252, 12
	v_readlane_b32 s61, v252, 13
	v_readlane_b32 s62, v252, 14
	v_readlane_b32 s63, v252, 15
	s_waitcnt vmcnt(3)
	ds_write2_b32 v12, v100, v101 offset1:1
	ds_write2_b32 v12, v102, v103 offset0:2 offset1:3
	s_nop 0
	s_nop 0
	s_nop 0
	s_nop 0
	s_nop 0
	s_waitcnt vmcnt(2)
	ds_write2_b32 v3, v110, v111 offset1:1
	s_nop 0
	s_nop 0
	s_nop 0
	v_add_u32_e32 v3, 0x1048, v12
	s_nop 0
	ds_write2_b32 v3, v112, v113 offset1:1
	s_nop 0
	v_add_u32_e32 v3, 0x2080, v12
	s_waitcnt vmcnt(1)
	ds_write2_b32 v3, v120, v121 offset1:1
	s_nop 0
	s_nop 0
	s_nop 0
	v_add_u32_e32 v3, 0x2088, v12
	s_nop 0
	ds_write2_b32 v3, v122, v123 offset1:1
	s_nop 0
	v_add_u32_e32 v3, 0x30c0, v12
	s_waitcnt vmcnt(0)
	ds_write2_b32 v3, v154, v155 offset1:1
	v_add_u32_e32 v3, 0x30c8, v12
	ds_write2_b32 v3, v156, v157 offset1:1
	v_ashrrev_i32_e32 v3, 2, v1
	v_and_b32_e32 v1, -4, v1
	v_mad_u32_u24 v1, v14, s13, v1
	s_waitcnt lgkmcnt(0)
	v_mov_b32_e32 v4, v154
	v_mov_b32_e32 v5, v155
	v_mov_b32_e32 v6, v156
	v_mov_b32_e32 v7, v157
	s_barrier
	ds_read2_b32 v[4:5], v1 offset1:65
	ds_read2_b32 v[6:7], v1 offset0:130 offset1:195
	v_add_u32_e32 v8, 0x400, v1
	v_add_u32_e32 v10, 0x800, v1
	v_add_u32_e32 v1, 0xc00, v1
	s_waitcnt lgkmcnt(1)
	v_cvt_pk_bf16_f32 v4, v4, v5
	s_waitcnt lgkmcnt(0)
	v_cvt_pk_bf16_f32 v5, v6, v7
	ds_read2_b32 v[6:7], v8 offset0:4 offset1:69
	ds_read2_b32 v[8:9], v8 offset0:134 offset1:199
	ds_read2_b32 v[12:13], v1 offset0:142 offset1:207
	s_waitcnt lgkmcnt(2)
	v_cvt_pk_bf16_f32 v6, v6, v7
	s_waitcnt lgkmcnt(1)
	v_cvt_pk_bf16_f32 v7, v8, v9
	ds_read2_b32 v[8:9], v10 offset0:8 offset1:73
	ds_read2_b32 v[10:11], v10 offset0:138 offset1:203
	s_waitcnt lgkmcnt(1)
	v_cvt_pk_bf16_f32 v8, v8, v9
	s_waitcnt lgkmcnt(0)
	v_cvt_pk_bf16_f32 v9, v10, v11
	ds_read2_b32 v[10:11], v1 offset0:12 offset1:77
	s_waitcnt lgkmcnt(0)
	v_cvt_pk_bf16_f32 v10, v10, v11
	v_cvt_pk_bf16_f32 v11, v12, v13
	v_add_u32_e32 v12, s12, v3
	v_ashrrev_i32_e32 v13, 31, v12
	v_lshlrev_b64 v[12:13], 9, v[12:13]
	v_lshl_add_u64 v[12:13], s[38:39], 0, v[12:13]
	v_lshl_add_u64 v[12:13], v[12:13], 0, s[34:35]
	v_lshl_add_u64 v[12:13], v[12:13], 0, v[182:183]
	global_store_dwordx4 v[12:13], v[4:7], off
	global_store_dwordx4 v[12:13], v[8:11], off offset:16

; DI unsigned pk2(float a, float b) { f32x2_t f = {a, b}; return __builtin_bit_cast(unsigned, __builtin_convertvector(f, bf16x2_t)); }
; DI void tconv_tile(const float* __restrict__ src, long lds, int cvalid, u16* __restrict__ dst, long ldd, int r0, int c0, char* smem) {
;     ...
;   __syncthreads();
;   const int lr = tid >> 4, lc = (tid & 15) * 4;
; #pragma unroll
;   for (int i = 0; i < 4; ++i) {
;     const int r = lr + 16 * i;
;     float4 v = make_float4(0.f, 0.f, 0.f, 0.f);
;     if (c0 + lc < cvalid) v = *(const float4*)(src + (long)(r0 + r) * lds + c0 + lc);
;     T[r][lc] = v.x; T[r][lc + 1] = v.y; T[r][lc + 2] = v.z; T[r][lc + 3] = v.w;
;   }
;   __syncthreads();
;   const int oc = tid >> 2, seg = (tid & 3) * 16;
;   unsigned pk[8];
; #pragma unroll
;   for (int k = 0; k < 8; ++k) pk[k] = pk2(T[seg + 2 * k][oc], T[seg + 2 * k + 1][oc]);
;   uint4* d = (uint4*)(dst + (long)(c0 + oc) * ldd + r0 + seg);
;   d[0] = make_uint4(pk[0], pk[1], pk[2], pk[3]);
;   d[1] = make_uint4(pk[4], pk[5], pk[6], pk[7]);
; DI void convert_weights(const Params& p, int layer, char* smem) {
;     ...
;       } else if (t < 1792) {
;         const int u = t - 1280;
;         tconv_tile(p.w_out_even + (size_t)e * 2048 * 1024, 1024, 1024, W + WE_OUT, 2048, (u >> 4) * 64, (u & 15) * 64, smem);
.LBB0_1774:
	s_andn2_b64 vcc, exec, s[38:39]
	s_cbranch_vccnz .LBB0_1776
	s_and_b32 s12, s5, 0x3c0
	v_mov_b32_e32 v1, v185
	v_readlane_b32 s56, v252, 8
	s_and_b32 s11, s10, 0x7fffffc0
	s_lshl_b32 s13, s12, 2
	v_ashrrev_i32_e32 v3, 4, v1
	v_readlane_b32 s68, v252, 20
	v_lshlrev_b32_e32 v14, 4, v1
	v_readlane_b32 s69, v252, 21
	s_add_u32 s14, s68, s13
	v_add_u32_e32 v10, s11, v3
	v_and_b32_e32 v182, 0xf0, v14
	s_addc_u32 s15, s69, 0
	v_ashrrev_i32_e32 v11, 31, v10
	v_lshl_add_u64 v[8:9], s[14:15], 0, v[182:183]
	v_lshlrev_b64 v[4:5], 12, v[10:11]
	v_lshl_add_u64 v[4:5], v[8:9], 0, v[4:5]
	s_waitcnt lgkmcnt(0)
	s_barrier
	global_load_dwordx4 v[100:103], v[4:5], off
	v_add_u32_e32 v104, 16, v10
	v_ashrrev_i32_e32 v105, 31, v104
	v_lshlrev_b64 v[106:107], 12, v[104:105]
	v_lshl_add_u64 v[108:109], v[8:9], 0, v[106:107]
	global_load_dwordx4 v[110:113], v[108:109], off
	v_add_u32_e32 v114, 32, v10
	v_ashrrev_i32_e32 v115, 31, v114
	v_lshlrev_b64 v[116:117], 12, v[114:115]
	v_lshl_add_u64 v[118:119], v[8:9], 0, v[116:117]
	global_load_dwordx4 v[120:123], v[118:119], off
	v_add_u32_e32 v124, 48, v10
	v_ashrrev_i32_e32 v125, 31, v124
	v_lshlrev_b64 v[126:127], 12, v[124:125]
	v_lshl_add_u64 v[128:129], v[8:9], 0, v[126:127]
	global_load_dwordx4 v[154:157], v[128:129], off
	s_nop 0
	s_movk_i32 s13, 0x104
	v_mad_u64_u32 v[12:13], s[14:15], v3, s13, v[182:183]
	v_add_u32_e32 v3, 0x1040, v12
	v_and_b32_e32 v14, 48, v14
	s_lshl_b32 s34, s11, 1
	v_readlane_b32 s64, v252, 16
	v_readlane_b32 s65, v252, 17
	v_readlane_b32 s66, v252, 18
	v_readlane_b32 s67, v252, 19
	v_readlane_b32 s70, v252, 22
	v_readlane_b32 s71, v252, 23
	v_lshlrev_b32_e32 v182, 1, v14
	s_mov_b32 s65, 0x2aaaaaab
	s_mov_b64 s[66:67], 0x5a8080
	s_movk_i32 s64, 0x41ff
	s_mov_b64 s[70:71], s[26:27]
	s_mov_b64 s[68:69], s[24:25]
	v_readlane_b32 s57, v252, 9
	v_readlane_b32 s58, v252, 10
	v_readlane_b32 s59, v252, 11
	v_readlane_b32 s60, v252, 12
	v_readlane_b32 s61, v252, 13
	v_readlane_b32 s62, v252, 14
	v_readlane_b32 s63, v252, 15
	s_waitcnt vmcnt(3)
	ds_write2_b32 v12, v100, v101 offset1:1
	ds_write2_b32 v12, v102, v103 offset0:2 offset1:3
	s_nop 0
	s_nop 0
	s_nop 0
	s_nop 0
	s_nop 0
	s_waitcnt vmcnt(2)
	ds_write2_b32 v3, v110, v111 offset1:1
	s_nop 0
	s_nop 0
	s_nop 0
	v_add_u32_e32 v3, 0x1048, v12
	s_nop 0
	ds_write2_b32 v3, v112, v113 offset1:1
	s_nop 0
	v_add_u32_e32 v3, 0x2080, v12
	s_waitcnt vmcnt(1)
	ds_write2_b32 v3, v120, v121 offset1:1
	s_nop 0
	s_nop 0
	s_nop 0
	v_add_u32_e32 v3, 0x2088, v12
	s_nop 0
	ds_write2_b32 v3, v122, v123 offset1:1
	s_nop 0
	v_add_u32_e32 v3, 0x30c0, v12
	s_waitcnt vmcnt(0)
	ds_write2_b32 v3, v154, v155 offset1:1
	v_add_u32_e32 v3, 0x30c8, v12
	ds_write2_b32 v3, v156, v157 offset1:1
	v_ashrrev_i32_e32 v3, 2, v1
	v_and_b32_e32 v1, -4, v1
	v_mad_u32_u24 v1, v14, s13, v1
	s_waitcnt lgkmcnt(0)
	v_mov_b32_e32 v4, v154
	v_mov_b32_e32 v5, v155
	v_mov_b32_e32 v6, v156
	v_mov_b32_e32 v7, v157
	s_barrier
	ds_read2_b32 v[4:5], v1 offset1:65
	ds_read2_b32 v[6:7], v1 offset0:130 offset1:195
	v_add_u32_e32 v8, 0x400, v1
	v_add_u32_e32 v10, 0x800, v1
	v_add_u32_e32 v1, 0xc00, v1
	s_waitcnt lgkmcnt(1)
	v_cvt_pk_bf16_f32 v4, v4, v5
	s_waitcnt lgkmcnt(0)
	v_cvt_pk_bf16_f32 v5, v6, v7
	ds_read2_b32 v[6:7], v8 offset0:4 offset1:69
	ds_read2_b32 v[8:9], v8 offset0:134 offset1:199
	ds_read2_b32 v[12:13], v1 offset0:142 offset1:207
	s_waitcnt lgkmcnt(2)
	v_cvt_pk_bf16_f32 v6, v6, v7
	s_waitcnt lgkmcnt(1)
	v_cvt_pk_bf16_f32 v7, v8, v9
	ds_read2_b32 v[8:9], v10 offset0:8 offset1:73
	ds_read2_b32 v[10:11], v10 offset0:138 offset1:203
	s_waitcnt lgkmcnt(1)
	v_cvt_pk_bf16_f32 v8, v8, v9
	s_waitcnt lgkmcnt(0)
	v_cvt_pk_bf16_f32 v9, v10, v11
	ds_read2_b32 v[10:11], v1 offset0:12 offset1:77
	s_waitcnt lgkmcnt(0)
	v_cvt_pk_bf16_f32 v10, v10, v11
	v_cvt_pk_bf16_f32 v11, v12, v13
	v_add_u32_e32 v12, s12, v3
	v_ashrrev_i32_e32 v13, 31, v12
	v_readlane_b32 s12, v252, 39
	v_lshlrev_b64 v[12:13], 12, v[12:13]
	v_readlane_b32 s13, v252, 40
	s_nop 1
	v_lshl_add_u64 v[12:13], s[12:13], 0, v[12:13]
	v_lshl_add_u64 v[12:13], v[12:13], 0, s[34:35]
	v_lshl_add_u64 v[12:13], v[12:13], 0, v[182:183]
	global_store_dwordx4 v[12:13], v[4:7], off
	global_store_dwordx4 v[12:13], v[8:11], off offset:16

; DI int get_bid() { int b = blockIdx.x; asm volatile("" : "+s"(b)); return b; }
; DI unsigned pk2(float a, float b) { f32x2_t f = {a, b}; return __builtin_bit_cast(unsigned, __builtin_convertvector(f, bf16x2_t)); }
; DI void tconv_tile(const float* __restrict__ src, long lds, int cvalid, u16* __restrict__ dst, long ldd, int r0, int c0, char* smem) {
;     ...
;   __syncthreads();
;   const int lr = tid >> 4, lc = (tid & 15) * 4;
; #pragma unroll
;   for (int i = 0; i < 4; ++i) {
;     const int r = lr + 16 * i;
;     float4 v = make_float4(0.f, 0.f, 0.f, 0.f);
;     if (c0 + lc < cvalid) v = *(const float4*)(src + (long)(r0 + r) * lds + c0 + lc);
;     T[r][lc] = v.x; T[r][lc + 1] = v.y; T[r][lc + 2] = v.z; T[r][lc + 3] = v.w;
;   }
;   __syncthreads();
;   const int oc = tid >> 2, seg = (tid & 3) * 16;
;   unsigned pk[8];
; #pragma unroll
;   for (int k = 0; k < 8; ++k) pk[k] = pk2(T[seg + 2 * k][oc], T[seg + 2 * k + 1][oc]);
;   uint4* d = (uint4*)(dst + (long)(c0 + oc) * ldd + r0 + seg);
;   d[0] = make_uint4(pk[0], pk[1], pk[2], pk[3]);
;   d[1] = make_uint4(pk[4], pk[5], pk[6], pk[7]);
; DI void convert_weights(const Params& p, int layer, char* smem) {
;     ...
;     for (int t = get_bid(); t < 1920; t += gridDim.x) {
;       if (t < 1280) {
;         tconv_tile(p.w_in_even + (size_t)e * 1024 * 5120, 5120, 5120, W + WE_IN, 1024, (t / 80) * 64, (t % 80) * 64, smem);
.LBB0_1777:
	s_andn2_b64 vcc, exec, s[38:39]
	s_cbranch_vccnz .LBB0_1766
	s_mul_hi_i32 s11, s4, 0x66666667
	s_lshr_b32 s12, s11, 31
	s_ashr_i32 s11, s11, 5
	s_add_i32 s11, s11, s12
	s_mul_i32 s12, s11, 0xffffec00
	s_add_i32 s12, s5, s12
	s_ashr_i32 s13, s12, 31
	v_readlane_b32 s56, v253, 21
	s_lshl_b32 s38, s11, 6
	v_mov_b32_e32 v1, v185
	s_lshl_b64 s[12:13], s[12:13], 2
	v_readlane_b32 s70, v253, 35
	v_readlane_b32 s71, v253, 36
	v_lshlrev_b32_e32 v12, 4, v1
	s_add_u32 s12, s70, s12
	v_ashrrev_i32_e32 v3, 4, v1
	v_and_b32_e32 v182, 0xf0, v12
	s_addc_u32 s13, s71, s13
	v_lshl_add_u64 v[8:9], s[12:13], 0, v[182:183]
	v_add_u32_e32 v13, s38, v3
	s_movk_i32 s15, 0x5000
	v_mad_i64_i32 v[4:5], s[12:13], v13, s15, v[8:9]
	s_waitcnt lgkmcnt(0)
	s_barrier
	global_load_dwordx4 v[100:103], v[4:5], off
	s_nop 0
	s_movk_i32 s14, 0x104
	v_mad_u64_u32 v[10:11], s[12:13], v3, s14, v[182:183]
	v_add_u32_e32 v3, 16, v13
	v_and_b32_e32 v14, 48, v12
	s_mulk_i32 s11, 0x1400
	s_ashr_i32 s39, s38, 31
	v_readlane_b32 s64, v253, 29
	v_readlane_b32 s65, v253, 30
	v_readlane_b32 s66, v253, 31
	v_readlane_b32 s67, v253, 32
	v_readlane_b32 s68, v253, 33
	v_readlane_b32 s69, v253, 34
	v_lshlrev_b32_e32 v182, 1, v14
	s_mov_b32 s65, 0x2aaaaaab
	s_mov_b64 s[66:67], 0x5a8080
	s_movk_i32 s64, 0x41ff
	s_mov_b64 s[68:69], s[24:25]
	s_mov_b64 s[70:71], s[26:27]
	v_readlane_b32 s57, v253, 22
	v_readlane_b32 s58, v253, 23
	v_readlane_b32 s59, v253, 24
	v_readlane_b32 s60, v253, 25
	v_readlane_b32 s61, v253, 26
	v_readlane_b32 s62, v253, 27
	v_readlane_b32 s63, v253, 28
	s_waitcnt vmcnt(0)
	ds_write2_b32 v10, v100, v101 offset1:1
	ds_write2_b32 v10, v102, v103 offset0:2 offset1:3
	v_mad_i64_i32 v[4:5], s[12:13], v3, s15, v[8:9]
	global_load_dwordx4 v[4:7], v[4:5], off
	v_add_u32_e32 v3, 0x1040, v10
	s_waitcnt vmcnt(0)
	ds_write2_b32 v3, v4, v5 offset1:1
	v_add_u32_e32 v3, 0x1048, v10
	ds_write2_b32 v3, v6, v7 offset1:1
	v_add_u32_e32 v3, 32, v13
	v_mad_i64_i32 v[4:5], s[12:13], v3, s15, v[8:9]
	global_load_dwordx4 v[4:7], v[4:5], off
	v_add_u32_e32 v3, 0x2080, v10
	s_waitcnt vmcnt(0)
	ds_write2_b32 v3, v4, v5 offset1:1
	v_add_u32_e32 v3, 0x2088, v10
	ds_write2_b32 v3, v6, v7 offset1:1
	v_add_u32_e32 v3, 48, v13
	v_mad_i64_i32 v[4:5], s[12:13], v3, s15, v[8:9]
	global_load_dwordx4 v[4:7], v[4:5], off
	v_add_u32_e32 v3, 0x30c0, v10
	s_waitcnt vmcnt(0)
	ds_write2_b32 v3, v4, v5 offset1:1
	v_add_u32_e32 v3, 0x30c8, v10
	ds_write2_b32 v3, v6, v7 offset1:1
	v_ashrrev_i32_e32 v3, 2, v1
	v_and_b32_e32 v1, -4, v1
	v_mad_u32_u24 v1, v14, s14, v1
	s_waitcnt lgkmcnt(0)
	s_barrier
	ds_read2_b32 v[4:5], v1 offset1:65
	ds_read2_b32 v[6:7], v1 offset0:130 offset1:195
	v_add_u32_e32 v8, 0x400, v1
	v_add_u32_e32 v10, 0x800, v1
	v_add_u32_e32 v1, 0xc00, v1
	s_waitcnt lgkmcnt(1)
	v_cvt_pk_bf16_f32 v4, v4, v5
	s_waitcnt lgkmcnt(0)
	v_cvt_pk_bf16_f32 v5, v6, v7
	ds_read2_b32 v[6:7], v8 offset0:4 offset1:69
	ds_read2_b32 v[8:9], v8 offset0:134 offset1:199
	ds_read2_b32 v[12:13], v1 offset0:142 offset1:207
	v_readlane_b32 s12, v255, 5
	v_readlane_b32 s16, v255, 9
	s_waitcnt lgkmcnt(2)
	v_cvt_pk_bf16_f32 v6, v6, v7
	s_waitcnt lgkmcnt(1)
	v_cvt_pk_bf16_f32 v7, v8, v9
	ds_read2_b32 v[8:9], v10 offset0:8 offset1:73
	ds_read2_b32 v[10:11], v10 offset0:138 offset1:203
	v_readlane_b32 s17, v255, 10
	v_readlane_b32 s13, v255, 6
	v_readlane_b32 s14, v255, 7
	s_waitcnt lgkmcnt(1)
	v_cvt_pk_bf16_f32 v8, v8, v9
	s_waitcnt lgkmcnt(0)
	v_cvt_pk_bf16_f32 v9, v10, v11
	ds_read2_b32 v[10:11], v1 offset0:12 offset1:77
	v_subrev_u32_e32 v1, s11, v3
	v_readlane_b32 s15, v255, 8
	v_readlane_b32 s18, v255, 11
	v_readlane_b32 s19, v255, 12
	s_waitcnt lgkmcnt(0)
	v_cvt_pk_bf16_f32 v10, v10, v11
	v_cvt_pk_bf16_f32 v11, v12, v13
	v_add_u32_e32 v12, s5, v1
	v_ashrrev_i32_e32 v13, 31, v12
	v_lshlrev_b64 v[12:13], 11, v[12:13]
	v_lshl_add_u64 v[12:13], s[16:17], 0, v[12:13]
	v_lshl_add_u64 v[12:13], s[38:39], 1, v[12:13]
	v_lshl_add_u64 v[12:13], v[12:13], 0, v[182:183]
	global_store_dwordx4 v[12:13], v[4:7], off
	global_store_dwordx4 v[12:13], v[8:11], off offset:16
	s_branch .LBB0_1766
